# rownorm x4 + finalnorm: hand-written pipelined fast paths (contiguous rows per wave, DPP reduce, cached modulation, no nt on re-read residual); attention: -m folded into QK accumulator, permlane32_swa
# speedup vs baseline: 1.0129x; 1.0129x over previous
; DI unsigned swz(int row, int chunk) { return (unsigned)row * 128u + (unsigned)((chunk ^ ((row >> 1) & 7)) << 4); }
; DI void attn_phase(const Params& P, unsigned char* lds) {
;     ...
;         f32x16 o[2];
; #pragma unroll
;         for (int r = 0; r < 16; ++r) { o[0][r] = 0.f; o[1][r] = 0.f; }
;         float m = -1e30f, l = 0.f;
;         const bf16_t* kbase = KB + (size_t)(b * 4 + kvh) * KVLEN * 64;
;         const bf16_t* vbase = VT + (size_t)(b * 4 + kvh) * 64 * KVLEN;
;         u32x4 rk[2], rv[2];
;         auto tile_of = [&](int i) __attribute__((always_inline)) { return (masked && i >= nW) ? 128 + (i - nW) : wlo + i + ((!masked && nW == 0) ? 128 : 0); };
;         {
;             const int p0 = tile_of(0) * 64;
; #pragma unroll
;             for (int j = 0; j < 2; ++j) { rk[j] = *(const u32x4*)(kbase + (size_t)(p0 + lr + 32 * j) * 64 + lc * 8); rv[j] = *(const u32x4*)(vbase + (size_t)(lr + 32 * j) * KVLEN + p0 + lc * 8); }
; #pragma unroll
;             for (int j = 0; j < 2; ++j) { *(u32x4*)(lds + swz(lr + 32 * j, lc)) = rk[j]; *(u32x4*)(lds + 8192 + swz(lr + 32 * j, lc)) = rv[j]; }
;         }
;         __syncthreads();
.LBB0_585:
	s_lshl_b32 s4, s6, 7
	s_add_i32 s10, s7, 4
	s_cmp_eq_u32 s7, 0
	v_add_u32_e32 v114, s19, v121
	s_cselect_b32 s11, 4, s7
	v_mad_i64_i32 v[0:1], s[0:1], v114, s3, v[108:109]
	s_cselect_b32 s29, 0x80, 0
	s_and_b64 s[0:1], s[16:17], exec
	v_lshl_add_u64 v[0:1], v[0:1], 0, s[4:5]
	s_cselect_b32 s4, s10, s11
	s_lshl_b32 s0, s18, 2
	s_add_i32 s10, s0, s27
	s_mul_i32 s0, s10, 0x108000
	s_mul_hi_u32 s1, s10, 0x108000
	s_add_u32 s0, s94, s0
	s_addc_u32 s1, s95, s1
	s_cmp_lt_i32 s7, 1
	s_cselect_b64 s[18:19], -1, 0
	s_and_b64 s[18:19], s[16:17], s[18:19]
	s_sub_i32 s11, 0x80, s7
	s_and_b64 s[30:31], s[16:17], exec
	s_cselect_b32 s63, 0, s29
	s_add_i32 s63, s63, s28
	s_and_b64 s[18:19], s[18:19], exec
	s_cselect_b32 s11, s11, s63
	v_lshl_add_u32 v2, s11, 6, v101
	v_mad_u64_u32 v[116:117], s[18:19], s10, v145, v[102:103]
	s_lshl_b32 s10, s11, 7
	s_add_u32 s18, s0, s10
	v_ashrrev_i32_e32 v3, 31, v2
	s_addc_u32 s19, s1, 0
	v_lshlrev_b64 v[2:3], 7, v[2:3]
	v_lshl_add_u64 v[4:5], s[18:19], 0, v[112:113]
	v_lshl_add_u64 v[2:3], v[116:117], 0, v[2:3]
	v_lshl_add_u64 v[6:7], v[4:5], 0, v[104:105]
	global_load_dwordx4 v[82:85], v[2:3], off
	global_load_dwordx4 v[86:89], v[6:7], off
	v_add_co_u32_e32 v2, vcc, s34, v2
	v_lshl_add_u64 v[0:1], v[0:1], 0, v[110:111]
	s_nop 0
	v_addc_co_u32_e32 v3, vcc, 0, v3, vcc
	v_lshl_add_u64 v[4:5], v[4:5], 0, v[106:107]
	global_load_dwordx4 v[90:93], v[2:3], off
	global_load_dwordx4 v[94:97], v[4:5], off
	global_load_dwordx4 v[66:69], v[0:1], off
	global_load_dwordx4 v[70:73], v[0:1], off offset:32
	global_load_dwordx4 v[74:77], v[0:1], off offset:64
	global_load_dwordx4 v[78:81], v[0:1], off offset:96
	s_cmp_lt_i32 s4, 1
	s_mov_b32 s28, 0
	s_waitcnt vmcnt(7)
	ds_write_b128 v122, v[82:85]
	s_waitcnt vmcnt(6)
	ds_write_b128 v122, v[86:89] offset:8192
	s_waitcnt vmcnt(5)
	ds_write_b128 v122, v[90:93] offset:4096
	s_waitcnt vmcnt(0)
	ds_write_b128 v122, v[94:97] offset:12288
	s_waitcnt lgkmcnt(0)
	s_barrier
	s_cbranch_scc1 .LBB0_601
	v_add_u32_e32 v0, s26, v120
	v_mov_b32_e32 v14, v99
	v_mov_b32_e32 v15, v99
	v_add_u32_e32 v33, 0x9f, v0
	v_add_u32_e32 v115, 0xffffff80, v0
	v_add_u32_e32 v148, v124, v0
	v_mov_b32_e32 v0, v99
	v_mov_b32_e32 v1, v99
	v_mov_b32_e32 v2, v99
	v_mov_b32_e32 v3, v99
	v_mov_b32_e32 v4, v99
	v_mov_b32_e32 v5, v99
	v_mov_b32_e32 v6, v99
	v_mov_b32_e32 v7, v99
	v_mov_b32_e32 v8, v99
	v_mov_b32_e32 v9, v99
	v_mov_b32_e32 v10, v99
	v_mov_b32_e32 v11, v99
	v_mov_b32_e32 v12, v99
	v_mov_b32_e32 v13, v99
	v_mov_b64_e32 v[30:31], v[14:15]
	v_lshl_add_u64 v[118:119], s[0:1], 0, v[112:113]
	s_sub_i32 s70, 0, s7
	v_mov_b32_e32 v149, 0
	v_mov_b32_e32 v172, 0
	v_mov_b32_e32 v173, 0
	v_mov_b32_e32 v174, 0
	v_mov_b32_e32 v175, 0
	v_mov_b32_e32 v176, 0
	v_mov_b32_e32 v177, 0
	v_mov_b32_e32 v178, 0
	v_mov_b32_e32 v179, 0
	v_mov_b32_e32 v180, 0
	v_mov_b32_e32 v181, 0
	v_mov_b32_e32 v182, 0
	v_mov_b32_e32 v183, 0
	v_mov_b32_e32 v184, 0
	v_mov_b32_e32 v185, 0
	v_mov_b32_e32 v186, 0
	v_mov_b32_e32 v187, 0
	v_mov_b32_e32 v188, 0xff800000
	v_mov_b32_e32 v32, 0
	s_movk_i32 s71, 0x4000
	v_mov_b64_e32 v[28:29], v[12:13]
	v_mov_b64_e32 v[26:27], v[10:11]
	v_mov_b64_e32 v[24:25], v[8:9]
	v_mov_b64_e32 v[22:23], v[6:7]
	v_mov_b64_e32 v[20:21], v[4:5]
	v_mov_b64_e32 v[18:19], v[2:3]
	v_mov_b64_e32 v[16:17], v[0:1]

; DI unsigned swz(int row, int chunk) { return (unsigned)row * 128u + (unsigned)((chunk ^ ((row >> 1) & 7)) << 4); }
; #define MFMA32(a, b, c) __builtin_amdgcn_mfma_f32_32x32x16_bf16((a), (b), (c), 0, 0, 0)
; DI int crow(int r, int hi) { return (r & 3) + 8 * (r >> 2) + 4 * hi; }
; DI void attn_phase(const Params& P, unsigned char* lds) {
;     ...
;                 f32x16 s[2];
;                 __builtin_amdgcn_s_setprio(1);
; #pragma unroll
;                 for (int kt = 0; kt < 2; ++kt) {
; #pragma unroll
;                     for (int r = 0; r < 16; ++r) s[kt][r] = 0.f;
; #pragma unroll
;                     for (int ks = 0; ks < 4; ++ks) { const bf16x8 kf = *(const bf16x8*)(cur + swz(32 * kt + l31, 2 * ks + lh)); s[kt] = MFMA32(kf, qf[ks], s[kt]); }
;                 }
;                 __builtin_amdgcn_s_setprio(0);
;                 if (wtile) {
; #pragma unroll
;                     for (int kt = 0; kt < 2; ++kt)
; #pragma unroll
;                         for (int r = 0; r < 16; ++r) { const int kp = p0 + 32 * kt + crow(r, lh); const int dlt = qpos - kp; if (dlt > 128 || dlt < -128) s[kt][r] = -INFINITY; }
;                 }
.LBB0_596:
	s_add_i32 s10, s71, 0xffffc000
	s_and_b32 s10, s10, 0x4000
	s_setprio 1
	v_or_b32_e32 v42, s10, v123
	v_add_u32_e32 v153, v42, v126
	ds_read_b128 v[34:37], v153
	ds_read_b128 v[38:41], v153 offset:4096
	v_add_u32_e32 v152, v42, v127
	v_add_u32_e32 v151, v42, v128
	v_add_u32_e32 v150, v42, v129
	s_waitcnt lgkmcnt(1)
	v_mfma_f32_32x32x16_bf16 v[50:65], v[34:37], v[66:69], v[172:187]
	ds_read_b128 v[34:37], v152
	ds_read_b128 v[154:157], v152 offset:4096
	ds_read_b128 v[158:161], v151 offset:4096
	s_waitcnt lgkmcnt(2)
	v_mfma_f32_32x32x16_bf16 v[50:65], v[34:37], v[70:73], v[50:65]
	ds_read_b128 v[34:37], v151
	s_waitcnt lgkmcnt(0)
	v_mfma_f32_32x32x16_bf16 v[50:65], v[34:37], v[74:77], v[50:65]
	ds_read_b128 v[34:37], v150
	ds_read_b128 v[162:165], v150 offset:4096
	s_waitcnt lgkmcnt(1)
	v_mfma_f32_32x32x16_bf16 v[50:65], v[34:37], v[78:81], v[50:65]
	v_mfma_f32_32x32x16_bf16 v[34:49], v[38:41], v[66:69], v[172:187]
	v_mfma_f32_32x32x16_bf16 v[34:49], v[154:157], v[70:73], v[34:49]
	v_mfma_f32_32x32x16_bf16 v[34:49], v[158:161], v[74:77], v[34:49]
	s_waitcnt lgkmcnt(0)
	v_mfma_f32_32x32x16_bf16 v[34:49], v[162:165], v[78:81], v[34:49]
	s_setprio 0
	s_andn2_b64 vcc, exec, s[28:29]
	s_cbranch_vccnz .LBB0_598
	v_subrev_u32_e32 v154, s75, v148
	v_sub_u32_e32 v155, v154, v100
	v_cmp_gt_u32_e32 vcc, s35, v155
	v_add_u32_e32 v156, v154, v130
	v_sub_u32_e32 v157, v154, v131
	v_cndmask_b32_e32 v50, v50, v147, vcc
	v_cmp_lt_u32_e32 vcc, s46, v156
	v_sub_u32_e32 v158, v154, v132
	v_sub_u32_e32 v159, v154, v133
	v_cndmask_b32_e32 v51, v147, v51, vcc
	v_cmp_lt_u32_e32 vcc, s46, v157
	v_sub_u32_e32 v160, v154, v134
	v_sub_u32_e32 v161, v154, v135
	v_cndmask_b32_e32 v52, v147, v52, vcc
	v_cmp_lt_u32_e32 vcc, s46, v158
	v_sub_u32_e32 v162, v154, v136
	v_sub_u32_e32 v163, v154, v137
	v_cndmask_b32_e32 v53, v147, v53, vcc
	v_cmp_lt_u32_e32 vcc, s46, v159
	v_sub_u32_e32 v164, v154, v138
	v_sub_u32_e32 v165, v154, v139
	v_cndmask_b32_e32 v54, v147, v54, vcc
	v_cmp_lt_u32_e32 vcc, s46, v160
	v_sub_u32_e32 v166, v154, v140
	v_sub_u32_e32 v167, v154, v141
	v_cndmask_b32_e32 v55, v147, v55, vcc
	v_cmp_lt_u32_e32 vcc, s46, v161
	v_sub_u32_e32 v168, v154, v142
	v_sub_u32_e32 v169, v154, v143
	v_cndmask_b32_e32 v56, v147, v56, vcc
	v_cmp_lt_u32_e32 vcc, s46, v162
	v_sub_u32_e32 v154, v154, v144
	v_subrev_u32_e32 v155, 32, v155
	v_cndmask_b32_e32 v57, v147, v57, vcc
	v_cmp_lt_u32_e32 vcc, s46, v163
	s_nop 1
	v_cndmask_b32_e32 v58, v147, v58, vcc
	v_cmp_lt_u32_e32 vcc, s46, v164
	s_nop 1
	v_cndmask_b32_e32 v59, v147, v59, vcc
	v_cmp_lt_u32_e32 vcc, s46, v165
	s_nop 1
	v_cndmask_b32_e32 v60, v147, v60, vcc
	v_cmp_lt_u32_e32 vcc, s46, v166
	s_nop 1
	v_cndmask_b32_e32 v61, v147, v61, vcc
	v_cmp_lt_u32_e32 vcc, s46, v167
	s_nop 1
	v_cndmask_b32_e32 v62, v147, v62, vcc
	v_cmp_lt_u32_e32 vcc, s46, v168
	s_nop 1
	v_cndmask_b32_e32 v63, v147, v63, vcc
	v_cmp_lt_u32_e32 vcc, s46, v169
	s_nop 1
	v_cndmask_b32_e32 v64, v147, v64, vcc
	v_cmp_lt_u32_e32 vcc, s46, v154
	v_subrev_u32_e32 v154, 32, v154
	s_nop 0
	v_cndmask_b32_e32 v65, v147, v65, vcc
	v_cmp_lt_u32_e32 vcc, s46, v155
	v_subrev_u32_e32 v155, 32, v156
	s_nop 0
	v_cndmask_b32_e32 v34, v147, v34, vcc
	v_cmp_lt_u32_e32 vcc, s46, v155
	v_subrev_u32_e32 v155, 32, v157
	s_nop 0
	v_cndmask_b32_e32 v35, v147, v35, vcc
	v_cmp_lt_u32_e32 vcc, s46, v155
	v_subrev_u32_e32 v155, 32, v158
	s_nop 0
	v_cndmask_b32_e32 v36, v147, v36, vcc
	v_cmp_lt_u32_e32 vcc, s46, v155
	v_subrev_u32_e32 v155, 32, v159
	s_nop 0
	v_cndmask_b32_e32 v37, v147, v37, vcc
	v_cmp_lt_u32_e32 vcc, s46, v155
	v_subrev_u32_e32 v155, 32, v160
	s_nop 0
	v_cndmask_b32_e32 v38, v147, v38, vcc
	v_cmp_lt_u32_e32 vcc, s46, v155
	v_subrev_u32_e32 v155, 32, v161
	s_nop 0
	v_cndmask_b32_e32 v39, v147, v39, vcc
	v_cmp_lt_u32_e32 vcc, s46, v155
	v_subrev_u32_e32 v155, 32, v162
	s_nop 0
	v_cndmask_b32_e32 v40, v147, v40, vcc
	v_cmp_lt_u32_e32 vcc, s46, v155
	v_subrev_u32_e32 v155, 32, v163
	s_nop 0
	v_cndmask_b32_e32 v41, v147, v41, vcc
	v_cmp_lt_u32_e32 vcc, s46, v155
	v_subrev_u32_e32 v155, 32, v164
	s_nop 0
	v_cndmask_b32_e32 v42, v147, v42, vcc
	v_cmp_lt_u32_e32 vcc, s46, v155
	v_subrev_u32_e32 v155, 32, v165
	s_nop 0
	v_cndmask_b32_e32 v43, v147, v43, vcc
	v_cmp_lt_u32_e32 vcc, s46, v155
	v_subrev_u32_e32 v155, 32, v166
	s_nop 0
	v_cndmask_b32_e32 v44, v147, v44, vcc
	v_cmp_lt_u32_e32 vcc, s46, v155
	v_subrev_u32_e32 v155, 32, v167
	s_nop 0
	v_cndmask_b32_e32 v45, v147, v45, vcc
	v_cmp_lt_u32_e32 vcc, s46, v155
	v_subrev_u32_e32 v155, 32, v168
	s_nop 0
	v_cndmask_b32_e32 v46, v147, v46, vcc
	v_cmp_lt_u32_e32 vcc, s46, v155
	v_subrev_u32_e32 v155, 32, v169
	s_nop 0
	v_cndmask_b32_e32 v47, v147, v47, vcc
	v_cmp_lt_u32_e32 vcc, s46, v155
	s_nop 1
	v_cndmask_b32_e32 v48, v147, v48, vcc
	v_cmp_lt_u32_e32 vcc, s46, v154
	s_nop 1
	v_cndmask_b32_e32 v49, v147, v49, vcc
; DI unsigned pk2(float lo, float hi) { const f32x2 v = {lo, hi}; return __builtin_bit_cast(unsigned, __builtin_convertvector(v, bf16x2v)); }
; DI unsigned swz(int row, int chunk) { return (unsigned)row * 128u + (unsigned)((chunk ^ ((row >> 1) & 7)) << 4); }
; #define MFMA32(a, b, c) __builtin_amdgcn_mfma_f32_32x32x16_bf16((a), (b), (c), 0, 0, 0)
; DI void attn_phase(const Params& P, unsigned char* lds) {
;     ...
;                 float mx = s[0][0];
; #pragma unroll
;                 for (int kt = 0; kt < 2; ++kt)
; #pragma unroll
;                     for (int r = 0; r < 16; ++r) mx = fmaxf(mx, s[kt][r]);
;                 mx = fmaxf(mx, __shfl_xor(mx, 32));
;                 const float mn = (mx > m + 8.0f) ? mx : m;
;                 if (__builtin_amdgcn_ballot_w64(mn != m) != 0ull) {
;                     const float alpha = __builtin_amdgcn_exp2f(m - mn);
;                     l *= alpha;
; #pragma unroll
;                     for (int r = 0; r < 16; ++r) { o[0][r] *= alpha; o[1][r] *= alpha; }
;                     m = mn;
;                 }
;                 float ps = 0.f;
; #pragma unroll
;                 for (int kt = 0; kt < 2; ++kt)
; #pragma unroll
;                     for (int r = 0; r < 16; ++r) { const float pv = __builtin_amdgcn_exp2f(s[kt][r] - mn); s[kt][r] = pv; ps += pv; }
;                 l += ps;
;                 __builtin_amdgcn_s_setprio(1);
; #pragma unroll
;                 for (int kt = 0; kt < 2; ++kt)
; #pragma unroll
;                     for (int sx = 0; sx < 2; ++sx) {
;                         union { u32x4 u; bf16x8 h; } pf;
;                         pf.u.x = pk2(s[kt][8 * sx + 0], s[kt][8 * sx + 1]); pf.u.y = pk2(s[kt][8 * sx + 2], s[kt][8 * sx + 3]);
;                         pf.u.z = pk2(s[kt][8 * sx + 4], s[kt][8 * sx + 5]); pf.u.w = pk2(s[kt][8 * sx + 6], s[kt][8 * sx + 7]);
; #pragma unroll
;                         for (int dt = 0; dt < 2; ++dt) { const bf16x8 vf = *(const bf16x8*)(cur + 8192 + swz(32 * dt + l31, 2 * (2 * kt + sx) + lh)); o[dt] = MFMA32(vf, pf.h, o[dt]); }
;                     }
;                 __builtin_amdgcn_s_setprio(0);
.LBB0_598:
	s_nop 3
	v_max_f32_e32 v154, v51, v51
	v_max_f32_e32 v155, v50, v50
	v_max_f32_e32 v154, v155, v154
	v_max3_f32 v154, v154, v52, v53
	v_max3_f32 v154, v154, v54, v55
	v_max3_f32 v154, v154, v56, v57
	v_max3_f32 v154, v154, v58, v59
	v_max3_f32 v154, v154, v60, v61
	v_max3_f32 v154, v154, v62, v63
	v_max3_f32 v154, v154, v64, v65
	v_max3_f32 v154, v154, v34, v35
	v_max3_f32 v154, v154, v36, v37
	v_max3_f32 v154, v154, v38, v39
	v_max3_f32 v154, v154, v40, v41
	v_max3_f32 v154, v154, v42, v43
	v_max3_f32 v154, v154, v44, v45
	v_max3_f32 v154, v154, v46, v47
	v_max3_f32 v154, v154, v48, v49
	v_mov_b32_e32 v155, v154
	s_nop 1
	v_permlane32_swap_b32_e32 v155, v154
	v_max_f32_e32 v154, v154, v155
	v_cmp_gt_f32_e32 vcc, v154, v188
	s_cbranch_vccz .LBB0_600
	v_mov_b32_e32 v155, 0x41000000
	s_nop 0
	v_cndmask_b32_e32 v154, v99, v154, vcc
	v_cndmask_b32_e32 v188, v188, v155, vcc
	v_max_f32_e32 v156, 0, v154
	v_add_f32_e32 v149, v149, v154
	v_exp_f32_e64 v156, -v156
	v_sub_f32_e32 v172, v172, v154
	v_sub_f32_e32 v173, v173, v154
	v_sub_f32_e32 v174, v174, v154
	v_sub_f32_e32 v175, v175, v154
	v_sub_f32_e32 v176, v176, v154
	v_sub_f32_e32 v177, v177, v154
	v_sub_f32_e32 v178, v178, v154
	v_sub_f32_e32 v179, v179, v154
	v_sub_f32_e32 v180, v180, v154
	v_sub_f32_e32 v181, v181, v154
	v_sub_f32_e32 v182, v182, v154
	v_sub_f32_e32 v183, v183, v154
	v_sub_f32_e32 v184, v184, v154
	v_sub_f32_e32 v185, v185, v154
	v_sub_f32_e32 v186, v186, v154
	v_sub_f32_e32 v187, v187, v154
	v_sub_f32_e32 v50, v50, v154
	v_sub_f32_e32 v51, v51, v154
	v_sub_f32_e32 v52, v52, v154
	v_sub_f32_e32 v53, v53, v154
	v_sub_f32_e32 v54, v54, v154
	v_sub_f32_e32 v55, v55, v154
	v_sub_f32_e32 v56, v56, v154
	v_sub_f32_e32 v57, v57, v154
	v_sub_f32_e32 v58, v58, v154
	v_sub_f32_e32 v59, v59, v154
	v_sub_f32_e32 v60, v60, v154
	v_sub_f32_e32 v61, v61, v154
	v_sub_f32_e32 v62, v62, v154
	v_sub_f32_e32 v63, v63, v154
	v_sub_f32_e32 v64, v64, v154
	v_sub_f32_e32 v65, v65, v154
	v_sub_f32_e32 v34, v34, v154
	v_sub_f32_e32 v35, v35, v154
	v_sub_f32_e32 v36, v36, v154
	v_sub_f32_e32 v37, v37, v154
	v_sub_f32_e32 v38, v38, v154
	v_sub_f32_e32 v39, v39, v154
	v_sub_f32_e32 v40, v40, v154
	v_sub_f32_e32 v41, v41, v154
	v_sub_f32_e32 v42, v42, v154
	v_sub_f32_e32 v43, v43, v154
	v_sub_f32_e32 v44, v44, v154
	v_sub_f32_e32 v45, v45, v154
	v_sub_f32_e32 v46, v46, v154
	v_sub_f32_e32 v47, v47, v154
	v_sub_f32_e32 v48, v48, v154
	v_sub_f32_e32 v49, v49, v154
	v_pk_mul_f32 v[30:31], v[30:31], v[156:157] op_sel_hi:[1,0]
	v_pk_mul_f32 v[28:29], v[28:29], v[156:157] op_sel_hi:[1,0]
	v_pk_mul_f32 v[26:27], v[26:27], v[156:157] op_sel_hi:[1,0]
	v_pk_mul_f32 v[24:25], v[24:25], v[156:157] op_sel_hi:[1,0]
	v_pk_mul_f32 v[22:23], v[22:23], v[156:157] op_sel_hi:[1,0]
	v_pk_mul_f32 v[20:21], v[20:21], v[156:157] op_sel_hi:[1,0]
	v_pk_mul_f32 v[18:19], v[18:19], v[156:157] op_sel_hi:[1,0]
	v_pk_mul_f32 v[16:17], v[16:17], v[156:157] op_sel_hi:[1,0]
	v_pk_mul_f32 v[14:15], v[14:15], v[156:157] op_sel_hi:[1,0]
	v_pk_mul_f32 v[12:13], v[12:13], v[156:157] op_sel_hi:[1,0]
	v_pk_mul_f32 v[10:11], v[10:11], v[156:157] op_sel_hi:[1,0]
	v_pk_mul_f32 v[8:9], v[8:9], v[156:157] op_sel_hi:[1,0]
	v_pk_mul_f32 v[6:7], v[6:7], v[156:157] op_sel_hi:[1,0]
	v_pk_mul_f32 v[4:5], v[4:5], v[156:157] op_sel_hi:[1,0]
	v_pk_mul_f32 v[2:3], v[2:3], v[156:157] op_sel_hi:[1,0]
	v_pk_mul_f32 v[0:1], v[0:1], v[156:157] op_sel_hi:[1,0]
	v_mul_f32_e32 v32, v32, v156
.LBB0_600:
	v_exp_f32_e32 v50, v50
	v_exp_f32_e32 v51, v51
	v_exp_f32_e32 v52, v52
	v_exp_f32_e32 v156, v34
	v_exp_f32_e32 v53, v53
	v_exp_f32_e32 v157, v35
	v_add_f32_e32 v155, 0, v50
	v_exp_f32_e32 v54, v54
	v_exp_f32_e32 v158, v36
	v_add_f32_e32 v155, v51, v155
	v_exp_f32_e32 v55, v55
	v_exp_f32_e32 v159, v37
	v_add_f32_e32 v155, v52, v155
	v_exp_f32_e32 v56, v56
	v_exp_f32_e32 v160, v38
	v_add_f32_e32 v155, v53, v155
	v_exp_f32_e32 v57, v57
	v_exp_f32_e32 v161, v39
	v_add_f32_e32 v155, v54, v155
	v_exp_f32_e32 v58, v58
	v_exp_f32_e32 v162, v40
	v_add_f32_e32 v155, v55, v155
	v_exp_f32_e32 v59, v59
	v_exp_f32_e32 v163, v41
	v_add_f32_e32 v155, v56, v155
	v_exp_f32_e32 v60, v60
	v_exp_f32_e32 v164, v42
	v_add_f32_e32 v155, v57, v155
	v_exp_f32_e32 v61, v61
	v_exp_f32_e32 v165, v43
	v_add_f32_e32 v155, v58, v155
	v_exp_f32_e32 v62, v62
	v_exp_f32_e32 v166, v44
	v_add_f32_e32 v155, v59, v155
	v_exp_f32_e32 v63, v63
	v_exp_f32_e32 v167, v45
	v_add_f32_e32 v155, v60, v155
	v_exp_f32_e32 v64, v64
	v_exp_f32_e32 v168, v46
	v_add_f32_e32 v155, v61, v155
	v_exp_f32_e32 v65, v65
	v_exp_f32_e32 v169, v47
	v_add_f32_e32 v155, v62, v155
	v_exp_f32_e32 v170, v48
	v_exp_f32_e32 v154, v49
	v_add_f32_e32 v34, v63, v155
	v_add_f32_e32 v34, v64, v34
	v_add_f32_e32 v155, v65, v34
	s_setprio 1
	ds_read_b128 v[34:37], v153 offset:8192
	ds_read_b128 v[42:45], v153 offset:12288
	v_cvt_pk_bf16_f32 v38, v50, v51
	v_cvt_pk_bf16_f32 v39, v52, v53
	v_cvt_pk_bf16_f32 v40, v54, v55
	v_cvt_pk_bf16_f32 v41, v56, v57
	v_add_f32_e32 v54, v156, v155
	v_add_f32_e32 v54, v157, v54
	v_cvt_pk_bf16_f32 v46, v164, v165
	s_waitcnt lgkmcnt(1)
	v_mfma_f32_32x32x16_bf16 v[16:31], v[34:37], v[38:41], v[16:31]
	ds_read_b128 v[34:37], v152 offset:8192
	v_cvt_pk_bf16_f32 v47, v166, v167
	v_cvt_pk_bf16_f32 v48, v168, v169
	v_cvt_pk_bf16_f32 v49, v170, v154
	s_waitcnt lgkmcnt(1)
	v_mfma_f32_32x32x16_bf16 v[0:15], v[42:45], v[38:41], v[0:15]
	ds_read_b128 v[42:45], v152 offset:12288
	v_cvt_pk_bf16_f32 v38, v58, v59
	v_cvt_pk_bf16_f32 v39, v60, v61
	v_cvt_pk_bf16_f32 v40, v62, v63
	v_cvt_pk_bf16_f32 v41, v64, v65
	s_waitcnt lgkmcnt(1)
	s_nop 0
	v_mfma_f32_32x32x16_bf16 v[16:31], v[34:37], v[38:41], v[16:31]
	ds_read_b128 v[34:37], v151 offset:8192
	s_waitcnt lgkmcnt(1)
	v_mfma_f32_32x32x16_bf16 v[0:15], v[42:45], v[38:41], v[0:15]
	ds_read_b128 v[42:45], v151 offset:12288
	v_cvt_pk_bf16_f32 v38, v156, v157
	v_cvt_pk_bf16_f32 v39, v158, v159
	v_cvt_pk_bf16_f32 v40, v160, v161
	v_cvt_pk_bf16_f32 v41, v162, v163
	s_waitcnt lgkmcnt(1)
	s_nop 0
	v_mfma_f32_32x32x16_bf16 v[16:31], v[34:37], v[38:41], v[16:31]
	ds_read_b128 v[34:37], v150 offset:8192
	ds_read_b128 v[50:53], v150 offset:12288
	s_waitcnt lgkmcnt(2)
	v_mfma_f32_32x32x16_bf16 v[0:15], v[42:45], v[38:41], v[0:15]
	v_add_f32_e32 v38, v158, v54
	v_add_f32_e32 v38, v159, v38
	v_add_f32_e32 v38, v160, v38
	v_add_f32_e32 v38, v161, v38
	v_add_f32_e32 v38, v162, v38
	v_add_f32_e32 v38, v163, v38
	v_add_f32_e32 v38, v164, v38
	s_waitcnt lgkmcnt(1)
	v_mfma_f32_32x32x16_bf16 v[16:31], v[34:37], v[46:49], v[16:31]
	v_add_f32_e32 v34, v165, v38
	v_add_f32_e32 v34, v166, v34
	v_add_f32_e32 v34, v167, v34
	v_add_f32_e32 v34, v168, v34
	v_add_f32_e32 v34, v169, v34
	v_add_f32_e32 v34, v170, v34
	v_add_f32_e32 v34, v154, v34
	s_waitcnt lgkmcnt(0)
	v_mfma_f32_32x32x16_bf16 v[0:15], v[50:53], v[46:49], v[0:15]
	v_add_f32_e32 v32, v34, v32
	s_setprio 0
	s_or_b64 exec, exec, s[0:1]
	s_andn2_b64 vcc, exec, s[26:27]
	s_cbranch_vccz .LBB0_592
	s_branch .LBB0_593

; DI int otid() { int t = threadIdx.x; asm volatile("" : "+v"(t)); return t; }
; DI void rownorm_phase(const float* srcL, const float* srcC, int M, const float* __restrict__ gain, const float* __restrict__ mod, int shift_idx, int scale_idx, bf16_t* __restrict__ H) {
;     const int lane = otid() & 63, wave = otid() >> 6;
;     for (int row = blockIdx.x * 4 + wave; row < M; row += gridDim.x * 4) {
;         const bool lat = row < NLAT;
;         const float* src = lat ? srcL + (size_t)row * DM : srcC + (size_t)(row - NLAT) * DM;
;         const float* mrow = mod + (lat ? (row >> 13) : 8) * 6144;
;         f32x4 v[4]; float ss = 0.f;
; #pragma unroll
;         for (int i = 0; i < 4; ++i) { v[i] = __builtin_nontemporal_load((const f32x4*)(src + (i * 64 + lane) * 4)); ss += v[i].x * v[i].x + v[i].y * v[i].y + v[i].z * v[i].z + v[i].w * v[i].w; }
; #pragma unroll
;         for (int o = 32; o > 0; o >>= 1) ss += __shfl_xor(ss, o);
;         const float rs = rsqrtf(ss * (1.0f / 1024.0f) + EPS);
.LBB0_687:
	s_or_b64 exec, exec, s[4:5]
	v_mov_b32_e32 v0, v216
	v_mov_b32_e32 v1, v216
	s_barrier
	v_readlane_b32 s3, v251, 38
	v_ashrrev_i32_e32 v1, 6, v1
	s_nop 0
	v_add_u32_e32 v16, s3, v1
	s_mov_b32 s3, 0x10800
	v_cmp_gt_i32_e32 vcc, s3, v16
	s_and_saveexec_b64 s[4:5], vcc
	s_cbranch_execz .LBB0_694
	s_cmpk_eq_i32 s33, 0x200
	s_cbranch_scc1 .Lrn2_fast
	v_lshlrev_b32_e32 v0, 2, v0
	v_and_b32_e32 v22, 0xfc, v0
	s_add_u32 s6, s76, 0x1000
	v_or_b32_e32 v24, 0x100, v22
	v_or_b32_e32 v26, 0x200, v22
	v_or_b32_e32 v28, 0x300, v22
	s_addc_u32 s7, s77, 0
	v_lshlrev_b32_e32 v0, 2, v22
	v_lshlrev_b32_e32 v4, 2, v24
	v_lshlrev_b32_e32 v8, 2, v26
	v_lshlrev_b32_e32 v12, 2, v28
	global_load_dwordx4 v[0:3], v0, s[6:7]
	s_nop 0
	global_load_dwordx4 v[4:7], v4, s[6:7]
	s_nop 0
	global_load_dwordx4 v[8:11], v8, s[6:7]
	s_nop 0
	global_load_dwordx4 v[12:15], v12, s[6:7]
	v_mbcnt_hi_u32_b32 v17, -1, v217
	v_and_b32_e32 v18, 64, v17
	v_add_u32_e32 v18, 64, v18
	v_xor_b32_e32 v20, 32, v17
	v_cmp_lt_i32_e32 vcc, v20, v18
	v_mov_b32_e32 v19, 0
	s_lshl_b32 s3, s33, 2
	v_cndmask_b32_e32 v20, v17, v20, vcc
	v_lshlrev_b32_e32 v32, 2, v20
	v_xor_b32_e32 v20, 16, v17
	v_cmp_lt_i32_e32 vcc, v20, v18
	s_mov_b64 s[6:7], 0
	s_mov_b32 s28, 0xffff
	v_cndmask_b32_e32 v20, v17, v20, vcc
	v_lshlrev_b32_e32 v33, 2, v20
	v_xor_b32_e32 v20, 8, v17
	v_cmp_lt_i32_e32 vcc, v20, v18
	v_mov_b32_e32 v23, v19
	v_mov_b32_e32 v38, 0x358637bd
	v_cndmask_b32_e32 v20, v17, v20, vcc
	v_lshlrev_b32_e32 v34, 2, v20
	v_xor_b32_e32 v20, 4, v17
	v_cmp_lt_i32_e32 vcc, v20, v18
	s_mov_b32 s29, 0x800000
	s_mov_b64 s[8:9], 0x4000
	v_cndmask_b32_e32 v20, v17, v20, vcc
	v_lshlrev_b32_e32 v35, 2, v20
	v_xor_b32_e32 v20, 2, v17
	v_cmp_lt_i32_e32 vcc, v20, v18
	s_mov_b64 s[14:15], 0x3000
	v_lshlrev_b32_e32 v24, 2, v24
	v_cndmask_b32_e32 v20, v17, v20, vcc
	v_lshlrev_b32_e32 v36, 2, v20
	v_xor_b32_e32 v20, 1, v17
	v_cmp_lt_i32_e32 vcc, v20, v18
	v_lshlrev_b32_e32 v18, 1, v22
	v_lshlrev_b32_e32 v22, 2, v22
	v_cndmask_b32_e32 v17, v17, v20, vcc
	v_lshlrev_b32_e32 v37, 2, v17
	v_lshl_add_u64 v[20:21], s[24:25], 0, v[18:19]
	v_mov_b32_e32 v25, v19
	v_lshlrev_b32_e32 v26, 2, v26
	v_mov_b32_e32 v27, v19
	v_lshlrev_b32_e32 v28, 2, v28
	v_mov_b32_e32 v29, v19
	s_mov_b32 s30, 0x107ff
	s_branch .LBB0_690

; DI unsigned pk2(float lo, float hi) { const f32x2 v = {lo, hi}; return __builtin_bit_cast(unsigned, __builtin_convertvector(v, bf16x2v)); }
; DI int otid() { int t = threadIdx.x; asm volatile("" : "+v"(t)); return t; }
; DI void rownorm_phase(const float* srcL, const float* srcC, int M, const float* __restrict__ gain, const float* __restrict__ mod, int shift_idx, int scale_idx, bf16_t* __restrict__ H) {
;     const int lane = otid() & 63, wave = otid() >> 6;
;     for (int row = blockIdx.x * 4 + wave; row < M; row += gridDim.x * 4) {
;         const bool lat = row < NLAT;
;         const float* src = lat ? srcL + (size_t)row * DM : srcC + (size_t)(row - NLAT) * DM;
;         const float* mrow = mod + (lat ? (row >> 13) : 8) * 6144;
;         f32x4 v[4]; float ss = 0.f;
; #pragma unroll
;         for (int i = 0; i < 4; ++i) { v[i] = __builtin_nontemporal_load((const f32x4*)(src + (i * 64 + lane) * 4)); ss += v[i].x * v[i].x + v[i].y * v[i].y + v[i].z * v[i].z + v[i].w * v[i].w; }
; #pragma unroll
;         for (int o = 32; o > 0; o >>= 1) ss += __shfl_xor(ss, o);
;         const float rs = rsqrtf(ss * (1.0f / 1024.0f) + EPS);
; #pragma unroll
;         for (int i = 0; i < 4; ++i) {
;             const int col = (i * 64 + lane) * 4;
;             const f32x4 g = *(const f32x4*)(gain + col), sc = *(const f32x4*)(mrow + scale_idx * 1024 + col), sh = *(const f32x4*)(mrow + shift_idx * 1024 + col);
;             const f32x4 y = (v[i] * rs * g) * (sc + 1.0f) + sh;
;             u32x2 o; o.x = pk2(y.x, y.y); o.y = pk2(y.z, y.w);
;             *(u32x2*)(H + (size_t)row * DM + col) = o;
;         }
;     }
.Lrn2_fast:
	v_lshrrev_b32_e32 v20, 6, v216
	v_and_b32_e32 v21, 63, v216
	v_mov_b32_e32 v30, 0x358637bd
	v_readfirstlane_b32 s3, v20
	s_lshl_b32 s16, s2, 2
	v_lshlrev_b32_e32 v16, 4, v21
	v_lshlrev_b32_e32 v17, 3, v21
	s_add_u32 s3, s3, s16
	s_mul_i32 s3, s3, 33
	s_add_u32 s14, s3, 33
	s_add_u32 s6, s76, 0x1000
	s_addc_u32 s7, s77, 0
	s_mov_b32 s15, -1
	global_load_dwordx4 v[0:3], v16, s[6:7]
	global_load_dwordx4 v[4:7], v16, s[6:7] offset:1024
	global_load_dwordx4 v[8:11], v16, s[6:7] offset:2048
	global_load_dwordx4 v[12:15], v16, s[6:7] offset:3072
	s_cmp_lt_u32 s3, 0x10000
	s_cselect_b32 s16, s48, s26
	s_cselect_b32 s17, s49, s27
	s_and_b32 s6, s3, 0xffff
	s_lshr_b32 s7, s6, 20
	s_lshl_b32 s6, s6, 12
	s_add_u32 s6, s6, s16
	s_addc_u32 s7, s7, s17
	global_load_dwordx4 v[40:43], v16, s[6:7]
	global_load_dwordx4 v[44:47], v16, s[6:7] offset:1024
	global_load_dwordx4 v[48:51], v16, s[6:7] offset:2048
	global_load_dwordx4 v[52:55], v16, s[6:7] offset:3072
	s_add_u32 s16, s3, 1
	s_mov_b32 s8, s16
	s_cmp_lt_u32 s8, 0x10000
	s_cselect_b32 s16, s48, s26
	s_cselect_b32 s17, s49, s27
	s_and_b32 s6, s8, 0xffff
	s_lshr_b32 s7, s6, 20
	s_lshl_b32 s6, s6, 12
	s_add_u32 s6, s6, s16
	s_addc_u32 s7, s7, s17
	global_load_dwordx4 v[88:91], v16, s[6:7]
	global_load_dwordx4 v[92:95], v16, s[6:7] offset:1024
	global_load_dwordx4 v[96:99], v16, s[6:7] offset:2048
	global_load_dwordx4 v[100:103], v16, s[6:7] offset:3072
.Lrn2_loop:
	s_sub_u32 s9, s14, 1
	s_min_u32 s8, s3, s9
	s_lshr_b32 s16, s8, 13
	s_min_u32 s16, s16, 8
	s_cmp_eq_u32 s16, s15
	s_cbranch_scc1 .Lrn2_nomod0
	s_mov_b32 s15, s16
	s_mul_i32 s16, s16, 0x6000
	s_add_u32 s6, s12, s16
	s_addc_u32 s7, s13, 0
	s_add_u32 s6, s6, 0x4000
	s_addc_u32 s7, s7, 0
	global_load_dwordx4 v[56:59], v16, s[6:7]
	global_load_dwordx4 v[60:63], v16, s[6:7] offset:1024
	global_load_dwordx4 v[64:67], v16, s[6:7] offset:2048
	global_load_dwordx4 v[68:71], v16, s[6:7] offset:3072
	s_sub_u32 s6, s6, 0x1000
	s_subb_u32 s7, s7, 0
	global_load_dwordx4 v[72:75], v16, s[6:7]
	global_load_dwordx4 v[76:79], v16, s[6:7] offset:1024
	global_load_dwordx4 v[80:83], v16, s[6:7] offset:2048
	global_load_dwordx4 v[84:87], v16, s[6:7] offset:3072
	s_waitcnt vmcnt(4)
	v_pk_add_f32 v[56:57], v[56:57], 1.0 op_sel_hi:[1,0]
	v_pk_add_f32 v[58:59], v[58:59], 1.0 op_sel_hi:[1,0]
	v_pk_add_f32 v[60:61], v[60:61], 1.0 op_sel_hi:[1,0]
	v_pk_add_f32 v[62:63], v[62:63], 1.0 op_sel_hi:[1,0]
	v_pk_add_f32 v[64:65], v[64:65], 1.0 op_sel_hi:[1,0]
	v_pk_add_f32 v[66:67], v[66:67], 1.0 op_sel_hi:[1,0]
	v_pk_add_f32 v[68:69], v[68:69], 1.0 op_sel_hi:[1,0]
	v_pk_add_f32 v[70:71], v[70:71], 1.0 op_sel_hi:[1,0]
	s_waitcnt vmcnt(0)
.Lrn2_nomod0:
	s_waitcnt vmcnt(4)
	s_add_u32 s16, s3, 2
	s_min_u32 s9, s16, s9
	s_cmp_lt_u32 s9, 0x10000
	s_cselect_b32 s16, s48, s26
	s_cselect_b32 s17, s49, s27
	s_and_b32 s6, s9, 0xffff
	s_lshr_b32 s7, s6, 20
	s_lshl_b32 s6, s6, 12
	s_add_u32 s6, s6, s16
	s_addc_u32 s7, s7, s17
	global_load_dwordx4 v[104:107], v16, s[6:7]
	global_load_dwordx4 v[108:111], v16, s[6:7] offset:1024
	global_load_dwordx4 v[112:115], v16, s[6:7] offset:2048
	global_load_dwordx4 v[116:119], v16, s[6:7] offset:3072
	v_mul_f32_e32 v20, v41, v41
	v_fmac_f32_e32 v20, v40, v40
	v_fmac_f32_e32 v20, v42, v42
	v_fmac_f32_e32 v20, v43, v43
	v_mul_f32_e32 v21, v45, v45
	v_fmac_f32_e32 v21, v44, v44
	v_fmac_f32_e32 v21, v46, v46
	v_fmac_f32_e32 v21, v47, v47
	v_mul_f32_e32 v22, v49, v49
	v_fmac_f32_e32 v22, v48, v48
	v_fmac_f32_e32 v22, v50, v50
	v_fmac_f32_e32 v22, v51, v51
	v_mul_f32_e32 v23, v53, v53
	v_fmac_f32_e32 v23, v52, v52
	v_fmac_f32_e32 v23, v54, v54
	v_fmac_f32_e32 v23, v55, v55
	v_add_f32_e32 v28, v20, v21
	v_add_f32_e32 v28, v28, v22
	v_add_f32_e32 v28, v28, v23
	s_nop 1
	v_add_f32_dpp v28, v28, v28 quad_perm:[1,0,3,2] row_mask:0xf bank_mask:0xf
	s_nop 1
	v_add_f32_dpp v28, v28, v28 quad_perm:[2,3,0,1] row_mask:0xf bank_mask:0xf
	s_nop 1
	v_add_f32_dpp v28, v28, v28 row_half_mirror row_mask:0xf bank_mask:0xf
	s_nop 1
	v_add_f32_dpp v28, v28, v28 row_mirror row_mask:0xf bank_mask:0xf
	s_nop 1
	v_readlane_b32 s6, v28, 0
	v_readlane_b32 s7, v28, 16
	v_readlane_b32 s16, v28, 32
	v_readlane_b32 s17, v28, 48
	s_nop 1
	v_mov_b32_e32 v29, s6
	v_add_f32_e32 v29, s7, v29
	v_add_f32_e32 v29, s16, v29
	v_add_f32_e32 v29, s17, v29
	v_fmamk_f32 v29, v29, 0x3a800000, v30
	v_mul_f32_e32 v31, 0x4b800000, v29
	v_cmp_gt_f32_e32 vcc, 0x800000, v29
	s_nop 1
	v_cndmask_b32_e32 v29, v29, v31, vcc
	v_rsq_f32_e32 v29, v29
	s_nop 1
	v_mul_f32_e32 v31, 0x45800000, v29
	v_cndmask_b32_e32 v18, v29, v31, vcc
	s_nop 0
	v_pk_mul_f32 v[40:41], v[40:41], v[18:19] op_sel_hi:[1,0]
	v_pk_mul_f32 v[42:43], v[42:43], v[18:19] op_sel_hi:[1,0]
	v_pk_mul_f32 v[44:45], v[44:45], v[18:19] op_sel_hi:[1,0]
	v_pk_mul_f32 v[46:47], v[46:47], v[18:19] op_sel_hi:[1,0]
	v_pk_mul_f32 v[48:49], v[48:49], v[18:19] op_sel_hi:[1,0]
	v_pk_mul_f32 v[50:51], v[50:51], v[18:19] op_sel_hi:[1,0]
	v_pk_mul_f32 v[52:53], v[52:53], v[18:19] op_sel_hi:[1,0]
	v_pk_mul_f32 v[54:55], v[54:55], v[18:19] op_sel_hi:[1,0]
	v_pk_mul_f32 v[40:41], v[0:1], v[40:41]
	v_pk_mul_f32 v[42:43], v[2:3], v[42:43]
	v_pk_mul_f32 v[44:45], v[4:5], v[44:45]
	v_pk_mul_f32 v[46:47], v[6:7], v[46:47]
	v_pk_mul_f32 v[48:49], v[8:9], v[48:49]
	v_pk_mul_f32 v[50:51], v[10:11], v[50:51]
	v_pk_mul_f32 v[52:53], v[12:13], v[52:53]
	v_pk_mul_f32 v[54:55], v[14:15], v[54:55]
	v_pk_fma_f32 v[40:41], v[56:57], v[40:41], v[72:73]
	v_pk_fma_f32 v[42:43], v[58:59], v[42:43], v[74:75]
	v_pk_fma_f32 v[44:45], v[60:61], v[44:45], v[76:77]
	v_pk_fma_f32 v[46:47], v[62:63], v[46:47], v[78:79]
	v_pk_fma_f32 v[48:49], v[64:65], v[48:49], v[80:81]
	v_pk_fma_f32 v[50:51], v[66:67], v[50:51], v[82:83]
	v_pk_fma_f32 v[52:53], v[68:69], v[52:53], v[84:85]
	v_pk_fma_f32 v[54:55], v[70:71], v[54:55], v[86:87]
	v_cvt_pk_bf16_f32 v32, v40, v41
	v_cvt_pk_bf16_f32 v33, v42, v43
	v_cvt_pk_bf16_f32 v34, v44, v45
	v_cvt_pk_bf16_f32 v35, v46, v47
	v_cvt_pk_bf16_f32 v36, v48, v49
	v_cvt_pk_bf16_f32 v37, v50, v51
	v_cvt_pk_bf16_f32 v38, v52, v53
	v_cvt_pk_bf16_f32 v39, v54, v55
	s_lshl_b32 s16, s8, 11
	s_add_u32 s8, s24, s16
	s_addc_u32 s9, s25, 0
	global_store_dwordx2 v17, v[32:33], s[8:9]
	global_store_dwordx2 v17, v[34:35], s[8:9] offset:512
	global_store_dwordx2 v17, v[36:37], s[8:9] offset:1024
	global_store_dwordx2 v17, v[38:39], s[8:9] offset:1536
	s_add_u32 s3, s3, 1
	s_sub_u32 s9, s14, 1
	s_min_u32 s8, s3, s9
	s_lshr_b32 s16, s8, 13
	s_min_u32 s16, s16, 8
	s_cmp_eq_u32 s16, s15
	s_cbranch_scc1 .Lrn2_nomod1
; DI unsigned pk2(float lo, float hi) { const f32x2 v = {lo, hi}; return __builtin_bit_cast(unsigned, __builtin_convertvector(v, bf16x2v)); }
; DI void rownorm_phase(const float* srcL, const float* srcC, int M, const float* __restrict__ gain, const float* __restrict__ mod, int shift_idx, int scale_idx, bf16_t* __restrict__ H) {
;     ...
;         f32x4 v[4]; float ss = 0.f;
; #pragma unroll
;         for (int i = 0; i < 4; ++i) { v[i] = __builtin_nontemporal_load((const f32x4*)(src + (i * 64 + lane) * 4)); ss += v[i].x * v[i].x + v[i].y * v[i].y + v[i].z * v[i].z + v[i].w * v[i].w; }
; #pragma unroll
;         for (int o = 32; o > 0; o >>= 1) ss += __shfl_xor(ss, o);
;         const float rs = rsqrtf(ss * (1.0f / 1024.0f) + EPS);
; #pragma unroll
;         for (int i = 0; i < 4; ++i) {
;             const int col = (i * 64 + lane) * 4;
;             const f32x4 g = *(const f32x4*)(gain + col), sc = *(const f32x4*)(mrow + scale_idx * 1024 + col), sh = *(const f32x4*)(mrow + shift_idx * 1024 + col);
;             const f32x4 y = (v[i] * rs * g) * (sc + 1.0f) + sh;
;             u32x2 o; o.x = pk2(y.x, y.y); o.y = pk2(y.z, y.w);
;             *(u32x2*)(H + (size_t)row * DM + col) = o;
;         }
;     }
	s_mov_b32 s15, s16
	s_mul_i32 s16, s16, 0x6000
	s_add_u32 s6, s12, s16
	s_addc_u32 s7, s13, 0
	s_add_u32 s6, s6, 0x4000
	s_addc_u32 s7, s7, 0
	global_load_dwordx4 v[56:59], v16, s[6:7]
	global_load_dwordx4 v[60:63], v16, s[6:7] offset:1024
	global_load_dwordx4 v[64:67], v16, s[6:7] offset:2048
	global_load_dwordx4 v[68:71], v16, s[6:7] offset:3072
	s_sub_u32 s6, s6, 0x1000
	s_subb_u32 s7, s7, 0
	global_load_dwordx4 v[72:75], v16, s[6:7]
	global_load_dwordx4 v[76:79], v16, s[6:7] offset:1024
	global_load_dwordx4 v[80:83], v16, s[6:7] offset:2048
	global_load_dwordx4 v[84:87], v16, s[6:7] offset:3072
	s_waitcnt vmcnt(4)
	v_pk_add_f32 v[56:57], v[56:57], 1.0 op_sel_hi:[1,0]
	v_pk_add_f32 v[58:59], v[58:59], 1.0 op_sel_hi:[1,0]
	v_pk_add_f32 v[60:61], v[60:61], 1.0 op_sel_hi:[1,0]
	v_pk_add_f32 v[62:63], v[62:63], 1.0 op_sel_hi:[1,0]
	v_pk_add_f32 v[64:65], v[64:65], 1.0 op_sel_hi:[1,0]
	v_pk_add_f32 v[66:67], v[66:67], 1.0 op_sel_hi:[1,0]
	v_pk_add_f32 v[68:69], v[68:69], 1.0 op_sel_hi:[1,0]
	v_pk_add_f32 v[70:71], v[70:71], 1.0 op_sel_hi:[1,0]
	s_waitcnt vmcnt(0)
.Lrn2_nomod1:
	s_waitcnt vmcnt(4)
	s_add_u32 s16, s3, 2
	s_min_u32 s9, s16, s9
	s_cmp_lt_u32 s9, 0x10000
	s_cselect_b32 s16, s48, s26
	s_cselect_b32 s17, s49, s27
	s_and_b32 s6, s9, 0xffff
	s_lshr_b32 s7, s6, 20
	s_lshl_b32 s6, s6, 12
	s_add_u32 s6, s6, s16
	s_addc_u32 s7, s7, s17
	global_load_dwordx4 v[40:43], v16, s[6:7]
	global_load_dwordx4 v[44:47], v16, s[6:7] offset:1024
	global_load_dwordx4 v[48:51], v16, s[6:7] offset:2048
	global_load_dwordx4 v[52:55], v16, s[6:7] offset:3072
	v_mul_f32_e32 v20, v89, v89
	v_fmac_f32_e32 v20, v88, v88
	v_fmac_f32_e32 v20, v90, v90
	v_fmac_f32_e32 v20, v91, v91
	v_mul_f32_e32 v21, v93, v93
	v_fmac_f32_e32 v21, v92, v92
	v_fmac_f32_e32 v21, v94, v94
	v_fmac_f32_e32 v21, v95, v95
	v_mul_f32_e32 v22, v97, v97
	v_fmac_f32_e32 v22, v96, v96
	v_fmac_f32_e32 v22, v98, v98
	v_fmac_f32_e32 v22, v99, v99
	v_mul_f32_e32 v23, v101, v101
	v_fmac_f32_e32 v23, v100, v100
	v_fmac_f32_e32 v23, v102, v102
	v_fmac_f32_e32 v23, v103, v103
	v_add_f32_e32 v28, v20, v21
	v_add_f32_e32 v28, v28, v22
	v_add_f32_e32 v28, v28, v23
	s_nop 1
	v_add_f32_dpp v28, v28, v28 quad_perm:[1,0,3,2] row_mask:0xf bank_mask:0xf
	s_nop 1
	v_add_f32_dpp v28, v28, v28 quad_perm:[2,3,0,1] row_mask:0xf bank_mask:0xf
	s_nop 1
	v_add_f32_dpp v28, v28, v28 row_half_mirror row_mask:0xf bank_mask:0xf
	s_nop 1
	v_add_f32_dpp v28, v28, v28 row_mirror row_mask:0xf bank_mask:0xf
	s_nop 1
	v_readlane_b32 s6, v28, 0
	v_readlane_b32 s7, v28, 16
	v_readlane_b32 s16, v28, 32
	v_readlane_b32 s17, v28, 48
	s_nop 1
	v_mov_b32_e32 v29, s6
	v_add_f32_e32 v29, s7, v29
	v_add_f32_e32 v29, s16, v29
	v_add_f32_e32 v29, s17, v29
	v_fmamk_f32 v29, v29, 0x3a800000, v30
	v_mul_f32_e32 v31, 0x4b800000, v29
	v_cmp_gt_f32_e32 vcc, 0x800000, v29
	s_nop 1
	v_cndmask_b32_e32 v29, v29, v31, vcc
	v_rsq_f32_e32 v29, v29
	s_nop 1
	v_mul_f32_e32 v31, 0x45800000, v29
	v_cndmask_b32_e32 v18, v29, v31, vcc
	s_nop 0
	v_pk_mul_f32 v[88:89], v[88:89], v[18:19] op_sel_hi:[1,0]
	v_pk_mul_f32 v[90:91], v[90:91], v[18:19] op_sel_hi:[1,0]
	v_pk_mul_f32 v[92:93], v[92:93], v[18:19] op_sel_hi:[1,0]
	v_pk_mul_f32 v[94:95], v[94:95], v[18:19] op_sel_hi:[1,0]
	v_pk_mul_f32 v[96:97], v[96:97], v[18:19] op_sel_hi:[1,0]
	v_pk_mul_f32 v[98:99], v[98:99], v[18:19] op_sel_hi:[1,0]
	v_pk_mul_f32 v[100:101], v[100:101], v[18:19] op_sel_hi:[1,0]
	v_pk_mul_f32 v[102:103], v[102:103], v[18:19] op_sel_hi:[1,0]
	v_pk_mul_f32 v[88:89], v[0:1], v[88:89]
	v_pk_mul_f32 v[90:91], v[2:3], v[90:91]
	v_pk_mul_f32 v[92:93], v[4:5], v[92:93]
	v_pk_mul_f32 v[94:95], v[6:7], v[94:95]
	v_pk_mul_f32 v[96:97], v[8:9], v[96:97]
	v_pk_mul_f32 v[98:99], v[10:11], v[98:99]
	v_pk_mul_f32 v[100:101], v[12:13], v[100:101]
	v_pk_mul_f32 v[102:103], v[14:15], v[102:103]
	v_pk_fma_f32 v[88:89], v[56:57], v[88:89], v[72:73]
	v_pk_fma_f32 v[90:91], v[58:59], v[90:91], v[74:75]
	v_pk_fma_f32 v[92:93], v[60:61], v[92:93], v[76:77]
	v_pk_fma_f32 v[94:95], v[62:63], v[94:95], v[78:79]
	v_pk_fma_f32 v[96:97], v[64:65], v[96:97], v[80:81]
	v_pk_fma_f32 v[98:99], v[66:67], v[98:99], v[82:83]
	v_pk_fma_f32 v[100:101], v[68:69], v[100:101], v[84:85]
	v_pk_fma_f32 v[102:103], v[70:71], v[102:103], v[86:87]
	v_cvt_pk_bf16_f32 v32, v88, v89
	v_cvt_pk_bf16_f32 v33, v90, v91
	v_cvt_pk_bf16_f32 v34, v92, v93
	v_cvt_pk_bf16_f32 v35, v94, v95
	v_cvt_pk_bf16_f32 v36, v96, v97
	v_cvt_pk_bf16_f32 v37, v98, v99
	v_cvt_pk_bf16_f32 v38, v100, v101
	v_cvt_pk_bf16_f32 v39, v102, v103
	s_lshl_b32 s16, s8, 11
	s_add_u32 s8, s24, s16
	s_addc_u32 s9, s25, 0
	global_store_dwordx2 v17, v[32:33], s[8:9]
	global_store_dwordx2 v17, v[34:35], s[8:9] offset:512
	global_store_dwordx2 v17, v[36:37], s[8:9] offset:1024
	global_store_dwordx2 v17, v[38:39], s[8:9] offset:1536
	s_add_u32 s3, s3, 1
	s_sub_u32 s9, s14, 1
	s_min_u32 s8, s3, s9
	s_lshr_b32 s16, s8, 13
	s_min_u32 s16, s16, 8
	s_cmp_eq_u32 s16, s15
	s_cbranch_scc1 .Lrn2_nomod2
	s_mov_b32 s15, s16
	s_mul_i32 s16, s16, 0x6000
	s_add_u32 s6, s12, s16
	s_addc_u32 s7, s13, 0
	s_add_u32 s6, s6, 0x4000
	s_addc_u32 s7, s7, 0
	global_load_dwordx4 v[56:59], v16, s[6:7]
	global_load_dwordx4 v[60:63], v16, s[6:7] offset:1024
	global_load_dwordx4 v[64:67], v16, s[6:7] offset:2048
	global_load_dwordx4 v[68:71], v16, s[6:7] offset:3072
	s_sub_u32 s6, s6, 0x1000
	s_subb_u32 s7, s7, 0
	global_load_dwordx4 v[72:75], v16, s[6:7]
	global_load_dwordx4 v[76:79], v16, s[6:7] offset:1024
	global_load_dwordx4 v[80:83], v16, s[6:7] offset:2048
	global_load_dwordx4 v[84:87], v16, s[6:7] offset:3072
	s_waitcnt vmcnt(4)
	v_pk_add_f32 v[56:57], v[56:57], 1.0 op_sel_hi:[1,0]
	v_pk_add_f32 v[58:59], v[58:59], 1.0 op_sel_hi:[1,0]
	v_pk_add_f32 v[60:61], v[60:61], 1.0 op_sel_hi:[1,0]
	v_pk_add_f32 v[62:63], v[62:63], 1.0 op_sel_hi:[1,0]
	v_pk_add_f32 v[64:65], v[64:65], 1.0 op_sel_hi:[1,0]
	v_pk_add_f32 v[66:67], v[66:67], 1.0 op_sel_hi:[1,0]
	v_pk_add_f32 v[68:69], v[68:69], 1.0 op_sel_hi:[1,0]
	v_pk_add_f32 v[70:71], v[70:71], 1.0 op_sel_hi:[1,0]
	s_waitcnt vmcnt(0)
; DI unsigned pk2(float lo, float hi) { const f32x2 v = {lo, hi}; return __builtin_bit_cast(unsigned, __builtin_convertvector(v, bf16x2v)); }
; DI void rownorm_phase(const float* srcL, const float* srcC, int M, const float* __restrict__ gain, const float* __restrict__ mod, int shift_idx, int scale_idx, bf16_t* __restrict__ H) {
;     ...
;         f32x4 v[4]; float ss = 0.f;
; #pragma unroll
;         for (int i = 0; i < 4; ++i) { v[i] = __builtin_nontemporal_load((const f32x4*)(src + (i * 64 + lane) * 4)); ss += v[i].x * v[i].x + v[i].y * v[i].y + v[i].z * v[i].z + v[i].w * v[i].w; }
; #pragma unroll
;         for (int o = 32; o > 0; o >>= 1) ss += __shfl_xor(ss, o);
;         const float rs = rsqrtf(ss * (1.0f / 1024.0f) + EPS);
; #pragma unroll
;         for (int i = 0; i < 4; ++i) {
;             const int col = (i * 64 + lane) * 4;
;             const f32x4 g = *(const f32x4*)(gain + col), sc = *(const f32x4*)(mrow + scale_idx * 1024 + col), sh = *(const f32x4*)(mrow + shift_idx * 1024 + col);
;             const f32x4 y = (v[i] * rs * g) * (sc + 1.0f) + sh;
;             u32x2 o; o.x = pk2(y.x, y.y); o.y = pk2(y.z, y.w);
;             *(u32x2*)(H + (size_t)row * DM + col) = o;
;         }
;     }
.Lrn2_nomod2:
	s_waitcnt vmcnt(4)
	s_add_u32 s16, s3, 2
	s_min_u32 s9, s16, s9
	s_cmp_lt_u32 s9, 0x10000
	s_cselect_b32 s16, s48, s26
	s_cselect_b32 s17, s49, s27
	s_and_b32 s6, s9, 0xffff
	s_lshr_b32 s7, s6, 20
	s_lshl_b32 s6, s6, 12
	s_add_u32 s6, s6, s16
	s_addc_u32 s7, s7, s17
	global_load_dwordx4 v[88:91], v16, s[6:7]
	global_load_dwordx4 v[92:95], v16, s[6:7] offset:1024
	global_load_dwordx4 v[96:99], v16, s[6:7] offset:2048
	global_load_dwordx4 v[100:103], v16, s[6:7] offset:3072
	v_mul_f32_e32 v20, v105, v105
	v_fmac_f32_e32 v20, v104, v104
	v_fmac_f32_e32 v20, v106, v106
	v_fmac_f32_e32 v20, v107, v107
	v_mul_f32_e32 v21, v109, v109
	v_fmac_f32_e32 v21, v108, v108
	v_fmac_f32_e32 v21, v110, v110
	v_fmac_f32_e32 v21, v111, v111
	v_mul_f32_e32 v22, v113, v113
	v_fmac_f32_e32 v22, v112, v112
	v_fmac_f32_e32 v22, v114, v114
	v_fmac_f32_e32 v22, v115, v115
	v_mul_f32_e32 v23, v117, v117
	v_fmac_f32_e32 v23, v116, v116
	v_fmac_f32_e32 v23, v118, v118
	v_fmac_f32_e32 v23, v119, v119
	v_add_f32_e32 v28, v20, v21
	v_add_f32_e32 v28, v28, v22
	v_add_f32_e32 v28, v28, v23
	s_nop 1
	v_add_f32_dpp v28, v28, v28 quad_perm:[1,0,3,2] row_mask:0xf bank_mask:0xf
	s_nop 1
	v_add_f32_dpp v28, v28, v28 quad_perm:[2,3,0,1] row_mask:0xf bank_mask:0xf
	s_nop 1
	v_add_f32_dpp v28, v28, v28 row_half_mirror row_mask:0xf bank_mask:0xf
	s_nop 1
	v_add_f32_dpp v28, v28, v28 row_mirror row_mask:0xf bank_mask:0xf
	s_nop 1
	v_readlane_b32 s6, v28, 0
	v_readlane_b32 s7, v28, 16
	v_readlane_b32 s16, v28, 32
	v_readlane_b32 s17, v28, 48
	s_nop 1
	v_mov_b32_e32 v29, s6
	v_add_f32_e32 v29, s7, v29
	v_add_f32_e32 v29, s16, v29
	v_add_f32_e32 v29, s17, v29
	v_fmamk_f32 v29, v29, 0x3a800000, v30
	v_mul_f32_e32 v31, 0x4b800000, v29
	v_cmp_gt_f32_e32 vcc, 0x800000, v29
	s_nop 1
	v_cndmask_b32_e32 v29, v29, v31, vcc
	v_rsq_f32_e32 v29, v29
	s_nop 1
	v_mul_f32_e32 v31, 0x45800000, v29
	v_cndmask_b32_e32 v18, v29, v31, vcc
	s_nop 0
	v_pk_mul_f32 v[104:105], v[104:105], v[18:19] op_sel_hi:[1,0]
	v_pk_mul_f32 v[106:107], v[106:107], v[18:19] op_sel_hi:[1,0]
	v_pk_mul_f32 v[108:109], v[108:109], v[18:19] op_sel_hi:[1,0]
	v_pk_mul_f32 v[110:111], v[110:111], v[18:19] op_sel_hi:[1,0]
	v_pk_mul_f32 v[112:113], v[112:113], v[18:19] op_sel_hi:[1,0]
	v_pk_mul_f32 v[114:115], v[114:115], v[18:19] op_sel_hi:[1,0]
	v_pk_mul_f32 v[116:117], v[116:117], v[18:19] op_sel_hi:[1,0]
	v_pk_mul_f32 v[118:119], v[118:119], v[18:19] op_sel_hi:[1,0]
	v_pk_mul_f32 v[104:105], v[0:1], v[104:105]
	v_pk_mul_f32 v[106:107], v[2:3], v[106:107]
	v_pk_mul_f32 v[108:109], v[4:5], v[108:109]
	v_pk_mul_f32 v[110:111], v[6:7], v[110:111]
	v_pk_mul_f32 v[112:113], v[8:9], v[112:113]
	v_pk_mul_f32 v[114:115], v[10:11], v[114:115]
	v_pk_mul_f32 v[116:117], v[12:13], v[116:117]
	v_pk_mul_f32 v[118:119], v[14:15], v[118:119]
	v_pk_fma_f32 v[104:105], v[56:57], v[104:105], v[72:73]
	v_pk_fma_f32 v[106:107], v[58:59], v[106:107], v[74:75]
	v_pk_fma_f32 v[108:109], v[60:61], v[108:109], v[76:77]
	v_pk_fma_f32 v[110:111], v[62:63], v[110:111], v[78:79]
	v_pk_fma_f32 v[112:113], v[64:65], v[112:113], v[80:81]
	v_pk_fma_f32 v[114:115], v[66:67], v[114:115], v[82:83]
	v_pk_fma_f32 v[116:117], v[68:69], v[116:117], v[84:85]
	v_pk_fma_f32 v[118:119], v[70:71], v[118:119], v[86:87]
	v_cvt_pk_bf16_f32 v32, v104, v105
	v_cvt_pk_bf16_f32 v33, v106, v107
	v_cvt_pk_bf16_f32 v34, v108, v109
	v_cvt_pk_bf16_f32 v35, v110, v111
	v_cvt_pk_bf16_f32 v36, v112, v113
	v_cvt_pk_bf16_f32 v37, v114, v115
	v_cvt_pk_bf16_f32 v38, v116, v117
	v_cvt_pk_bf16_f32 v39, v118, v119
	s_lshl_b32 s16, s8, 11
	s_add_u32 s8, s24, s16
	s_addc_u32 s9, s25, 0
	global_store_dwordx2 v17, v[32:33], s[8:9]
	global_store_dwordx2 v17, v[34:35], s[8:9] offset:512
	global_store_dwordx2 v17, v[36:37], s[8:9] offset:1024
	global_store_dwordx2 v17, v[38:39], s[8:9] offset:1536
	s_add_u32 s3, s3, 1
	s_cmp_lt_u32 s3, s14
	s_cbranch_scc1 .Lrn2_loop

; DI int otid() { int t = threadIdx.x; asm volatile("" : "+v"(t)); return t; }
; DI void rownorm_phase(const float* srcL, const float* srcC, int M, const float* __restrict__ gain, const float* __restrict__ mod, int shift_idx, int scale_idx, bf16_t* __restrict__ H) {
;     const int lane = otid() & 63, wave = otid() >> 6;
;     for (int row = blockIdx.x * 4 + wave; row < M; row += gridDim.x * 4) {
;         const bool lat = row < NLAT;
;         const float* src = lat ? srcL + (size_t)row * DM : srcC + (size_t)(row - NLAT) * DM;
;         const float* mrow = mod + (lat ? (row >> 13) : 8) * 6144;
;         f32x4 v[4]; float ss = 0.f;
; #pragma unroll
;         for (int i = 0; i < 4; ++i) { v[i] = __builtin_nontemporal_load((const f32x4*)(src + (i * 64 + lane) * 4)); ss += v[i].x * v[i].x + v[i].y * v[i].y + v[i].z * v[i].z + v[i].w * v[i].w; }
; #pragma unroll
;         for (int o = 32; o > 0; o >>= 1) ss += __shfl_xor(ss, o);
;         const float rs = rsqrtf(ss * (1.0f / 1024.0f) + EPS);
.LBB0_823:
	s_or_b64 exec, exec, s[0:1]
	v_mov_b32_e32 v0, v216
	v_mov_b32_e32 v1, v216
	s_barrier
	v_readlane_b32 s0, v251, 38
	v_ashrrev_i32_e32 v1, 6, v1
	s_add_u32 s28, s50, 0x2f36000
	v_add_u32_e32 v16, s0, v1
	s_mov_b32 s0, 0x10800
	s_addc_u32 s29, s51, 0
	v_cmp_gt_i32_e32 vcc, s0, v16
	s_and_saveexec_b64 s[0:1], vcc
	s_cbranch_execz .LBB0_830
	s_cmpk_eq_i32 s33, 0x200
	s_cbranch_scc1 .Lrn3_fast
	v_lshlrev_b32_e32 v0, 2, v0
	v_and_b32_e32 v22, 0xfc, v0
	s_add_u32 s4, s76, 0x2000
	v_or_b32_e32 v24, 0x100, v22
	v_or_b32_e32 v26, 0x200, v22
	v_or_b32_e32 v28, 0x300, v22
	s_addc_u32 s5, s77, 0
	v_lshlrev_b32_e32 v0, 2, v22
	v_lshlrev_b32_e32 v4, 2, v24
	v_lshlrev_b32_e32 v8, 2, v26
	v_lshlrev_b32_e32 v12, 2, v28
	global_load_dwordx4 v[0:3], v0, s[4:5]
	s_nop 0
	global_load_dwordx4 v[4:7], v4, s[4:5]
	s_nop 0
	global_load_dwordx4 v[8:11], v8, s[4:5]
	s_nop 0
	global_load_dwordx4 v[12:15], v12, s[4:5]
	v_mbcnt_hi_u32_b32 v17, -1, v217
	v_and_b32_e32 v18, 64, v17
	v_add_u32_e32 v18, 64, v18
	v_xor_b32_e32 v20, 32, v17
	v_cmp_lt_i32_e32 vcc, v20, v18
	v_mov_b32_e32 v19, 0
	s_lshl_b32 s3, s33, 2
	v_cndmask_b32_e32 v20, v17, v20, vcc
	v_lshlrev_b32_e32 v32, 2, v20
	v_xor_b32_e32 v20, 16, v17
	v_cmp_lt_i32_e32 vcc, v20, v18
	s_mov_b64 s[4:5], 0
	s_mov_b32 s12, 0xffff
	v_cndmask_b32_e32 v20, v17, v20, vcc
	v_lshlrev_b32_e32 v33, 2, v20
	v_xor_b32_e32 v20, 8, v17
	v_cmp_lt_i32_e32 vcc, v20, v18
	v_mov_b32_e32 v23, v19
	v_mov_b32_e32 v38, 0x358637bd
	v_cndmask_b32_e32 v20, v17, v20, vcc
	v_lshlrev_b32_e32 v34, 2, v20
	v_xor_b32_e32 v20, 4, v17
	v_cmp_lt_i32_e32 vcc, v20, v18
	s_mov_b32 s13, 0x800000
	s_mov_b64 s[6:7], 0x1000
	v_cndmask_b32_e32 v20, v17, v20, vcc
	v_lshlrev_b32_e32 v35, 2, v20
	v_xor_b32_e32 v20, 2, v17
	v_cmp_lt_i32_e32 vcc, v20, v18
	v_lshlrev_b32_e32 v24, 2, v24
	v_mov_b32_e32 v25, v19
	v_cndmask_b32_e32 v20, v17, v20, vcc
	v_lshlrev_b32_e32 v36, 2, v20
	v_xor_b32_e32 v20, 1, v17
	v_cmp_lt_i32_e32 vcc, v20, v18
	v_lshlrev_b32_e32 v18, 1, v22
	v_lshlrev_b32_e32 v22, 2, v22
	v_cndmask_b32_e32 v17, v17, v20, vcc
	v_lshlrev_b32_e32 v37, 2, v17
	v_lshl_add_u64 v[20:21], s[24:25], 0, v[18:19]
	v_lshlrev_b32_e32 v26, 2, v26
	v_mov_b32_e32 v27, v19
	v_lshlrev_b32_e32 v28, 2, v28
	v_mov_b32_e32 v29, v19
	s_mov_b32 s14, 0x107ff
	s_branch .LBB0_826

; DI unsigned pk2(float lo, float hi) { const f32x2 v = {lo, hi}; return __builtin_bit_cast(unsigned, __builtin_convertvector(v, bf16x2v)); }
; DI int otid() { int t = threadIdx.x; asm volatile("" : "+v"(t)); return t; }
; DI void rownorm_phase(const float* srcL, const float* srcC, int M, const float* __restrict__ gain, const float* __restrict__ mod, int shift_idx, int scale_idx, bf16_t* __restrict__ H) {
;     const int lane = otid() & 63, wave = otid() >> 6;
;     for (int row = blockIdx.x * 4 + wave; row < M; row += gridDim.x * 4) {
;         const bool lat = row < NLAT;
;         const float* src = lat ? srcL + (size_t)row * DM : srcC + (size_t)(row - NLAT) * DM;
;         const float* mrow = mod + (lat ? (row >> 13) : 8) * 6144;
;         f32x4 v[4]; float ss = 0.f;
; #pragma unroll
;         for (int i = 0; i < 4; ++i) { v[i] = __builtin_nontemporal_load((const f32x4*)(src + (i * 64 + lane) * 4)); ss += v[i].x * v[i].x + v[i].y * v[i].y + v[i].z * v[i].z + v[i].w * v[i].w; }
; #pragma unroll
;         for (int o = 32; o > 0; o >>= 1) ss += __shfl_xor(ss, o);
;         const float rs = rsqrtf(ss * (1.0f / 1024.0f) + EPS);
; #pragma unroll
;         for (int i = 0; i < 4; ++i) {
;             const int col = (i * 64 + lane) * 4;
;             const f32x4 g = *(const f32x4*)(gain + col), sc = *(const f32x4*)(mrow + scale_idx * 1024 + col), sh = *(const f32x4*)(mrow + shift_idx * 1024 + col);
;             const f32x4 y = (v[i] * rs * g) * (sc + 1.0f) + sh;
;             u32x2 o; o.x = pk2(y.x, y.y); o.y = pk2(y.z, y.w);
;             *(u32x2*)(H + (size_t)row * DM + col) = o;
;         }
;     }
.Lrn3_fast:
	v_lshrrev_b32_e32 v20, 6, v216
	v_and_b32_e32 v21, 63, v216
	v_mov_b32_e32 v30, 0x358637bd
	v_readfirstlane_b32 s3, v20
	s_lshl_b32 s12, s2, 2
	v_lshlrev_b32_e32 v16, 4, v21
	v_lshlrev_b32_e32 v17, 3, v21
	s_add_u32 s3, s3, s12
	s_mul_i32 s3, s3, 33
	s_add_u32 s8, s3, 33
	s_add_u32 s4, s76, 0x2000
	s_addc_u32 s5, s77, 0
	s_mov_b32 s9, -1
	global_load_dwordx4 v[0:3], v16, s[4:5]
	global_load_dwordx4 v[4:7], v16, s[4:5] offset:1024
	global_load_dwordx4 v[8:11], v16, s[4:5] offset:2048
	global_load_dwordx4 v[12:15], v16, s[4:5] offset:3072
	s_cmp_lt_u32 s3, 0x10000
	s_cselect_b32 s12, s48, s26
	s_cselect_b32 s13, s49, s27
	s_and_b32 s4, s3, 0xffff
	s_lshr_b32 s5, s4, 20
	s_lshl_b32 s4, s4, 12
	s_add_u32 s4, s4, s12
	s_addc_u32 s5, s5, s13
	global_load_dwordx4 v[40:43], v16, s[4:5]
	global_load_dwordx4 v[44:47], v16, s[4:5] offset:1024
	global_load_dwordx4 v[48:51], v16, s[4:5] offset:2048
	global_load_dwordx4 v[52:55], v16, s[4:5] offset:3072
	s_add_u32 s12, s3, 1
	s_mov_b32 s6, s12
	s_cmp_lt_u32 s6, 0x10000
	s_cselect_b32 s12, s48, s26
	s_cselect_b32 s13, s49, s27
	s_and_b32 s4, s6, 0xffff
	s_lshr_b32 s5, s4, 20
	s_lshl_b32 s4, s4, 12
	s_add_u32 s4, s4, s12
	s_addc_u32 s5, s5, s13
	global_load_dwordx4 v[88:91], v16, s[4:5]
	global_load_dwordx4 v[92:95], v16, s[4:5] offset:1024
	global_load_dwordx4 v[96:99], v16, s[4:5] offset:2048
	global_load_dwordx4 v[100:103], v16, s[4:5] offset:3072
.Lrn3_loop:
	s_sub_u32 s7, s8, 1
	s_min_u32 s6, s3, s7
	s_lshr_b32 s12, s6, 13
	s_min_u32 s12, s12, 8
	s_cmp_eq_u32 s12, s9
	s_cbranch_scc1 .Lrn3_nomod0
	s_mov_b32 s9, s12
	s_mul_i32 s12, s12, 0x6000
	s_add_u32 s4, s28, s12
	s_addc_u32 s5, s29, 0
	s_add_u32 s4, s4, 0x1000
	s_addc_u32 s5, s5, 0
	global_load_dwordx4 v[56:59], v16, s[4:5]
	global_load_dwordx4 v[60:63], v16, s[4:5] offset:1024
	global_load_dwordx4 v[64:67], v16, s[4:5] offset:2048
	global_load_dwordx4 v[68:71], v16, s[4:5] offset:3072
	s_sub_u32 s4, s4, 0x1000
	s_subb_u32 s5, s5, 0
	global_load_dwordx4 v[72:75], v16, s[4:5]
	global_load_dwordx4 v[76:79], v16, s[4:5] offset:1024
	global_load_dwordx4 v[80:83], v16, s[4:5] offset:2048
	global_load_dwordx4 v[84:87], v16, s[4:5] offset:3072
	s_waitcnt vmcnt(4)
	v_pk_add_f32 v[56:57], v[56:57], 1.0 op_sel_hi:[1,0]
	v_pk_add_f32 v[58:59], v[58:59], 1.0 op_sel_hi:[1,0]
	v_pk_add_f32 v[60:61], v[60:61], 1.0 op_sel_hi:[1,0]
	v_pk_add_f32 v[62:63], v[62:63], 1.0 op_sel_hi:[1,0]
	v_pk_add_f32 v[64:65], v[64:65], 1.0 op_sel_hi:[1,0]
	v_pk_add_f32 v[66:67], v[66:67], 1.0 op_sel_hi:[1,0]
	v_pk_add_f32 v[68:69], v[68:69], 1.0 op_sel_hi:[1,0]
	v_pk_add_f32 v[70:71], v[70:71], 1.0 op_sel_hi:[1,0]
	s_waitcnt vmcnt(0)
.Lrn3_nomod0:
	s_waitcnt vmcnt(4)
	s_add_u32 s12, s3, 2
	s_min_u32 s7, s12, s7
	s_cmp_lt_u32 s7, 0x10000
	s_cselect_b32 s12, s48, s26
	s_cselect_b32 s13, s49, s27
	s_and_b32 s4, s7, 0xffff
	s_lshr_b32 s5, s4, 20
	s_lshl_b32 s4, s4, 12
	s_add_u32 s4, s4, s12
	s_addc_u32 s5, s5, s13
	global_load_dwordx4 v[104:107], v16, s[4:5]
	global_load_dwordx4 v[108:111], v16, s[4:5] offset:1024
	global_load_dwordx4 v[112:115], v16, s[4:5] offset:2048
	global_load_dwordx4 v[116:119], v16, s[4:5] offset:3072
	v_mul_f32_e32 v20, v41, v41
	v_fmac_f32_e32 v20, v40, v40
	v_fmac_f32_e32 v20, v42, v42
	v_fmac_f32_e32 v20, v43, v43
	v_mul_f32_e32 v21, v45, v45
	v_fmac_f32_e32 v21, v44, v44
	v_fmac_f32_e32 v21, v46, v46
	v_fmac_f32_e32 v21, v47, v47
	v_mul_f32_e32 v22, v49, v49
	v_fmac_f32_e32 v22, v48, v48
	v_fmac_f32_e32 v22, v50, v50
	v_fmac_f32_e32 v22, v51, v51
	v_mul_f32_e32 v23, v53, v53
	v_fmac_f32_e32 v23, v52, v52
	v_fmac_f32_e32 v23, v54, v54
	v_fmac_f32_e32 v23, v55, v55
	v_add_f32_e32 v28, v20, v21
	v_add_f32_e32 v28, v28, v22
	v_add_f32_e32 v28, v28, v23
	s_nop 1
	v_add_f32_dpp v28, v28, v28 quad_perm:[1,0,3,2] row_mask:0xf bank_mask:0xf
	s_nop 1
	v_add_f32_dpp v28, v28, v28 quad_perm:[2,3,0,1] row_mask:0xf bank_mask:0xf
	s_nop 1
	v_add_f32_dpp v28, v28, v28 row_half_mirror row_mask:0xf bank_mask:0xf
	s_nop 1
	v_add_f32_dpp v28, v28, v28 row_mirror row_mask:0xf bank_mask:0xf
	s_nop 1
	v_readlane_b32 s4, v28, 0
	v_readlane_b32 s5, v28, 16
	v_readlane_b32 s12, v28, 32
	v_readlane_b32 s13, v28, 48
	s_nop 1
	v_mov_b32_e32 v29, s4
	v_add_f32_e32 v29, s5, v29
	v_add_f32_e32 v29, s12, v29
	v_add_f32_e32 v29, s13, v29
	v_fmamk_f32 v29, v29, 0x3a800000, v30
	v_mul_f32_e32 v31, 0x4b800000, v29
	v_cmp_gt_f32_e32 vcc, 0x800000, v29
	s_nop 1
	v_cndmask_b32_e32 v29, v29, v31, vcc
	v_rsq_f32_e32 v29, v29
	s_nop 1
	v_mul_f32_e32 v31, 0x45800000, v29
	v_cndmask_b32_e32 v18, v29, v31, vcc
	s_nop 0
	v_pk_mul_f32 v[40:41], v[40:41], v[18:19] op_sel_hi:[1,0]
	v_pk_mul_f32 v[42:43], v[42:43], v[18:19] op_sel_hi:[1,0]
	v_pk_mul_f32 v[44:45], v[44:45], v[18:19] op_sel_hi:[1,0]
	v_pk_mul_f32 v[46:47], v[46:47], v[18:19] op_sel_hi:[1,0]
	v_pk_mul_f32 v[48:49], v[48:49], v[18:19] op_sel_hi:[1,0]
	v_pk_mul_f32 v[50:51], v[50:51], v[18:19] op_sel_hi:[1,0]
	v_pk_mul_f32 v[52:53], v[52:53], v[18:19] op_sel_hi:[1,0]
	v_pk_mul_f32 v[54:55], v[54:55], v[18:19] op_sel_hi:[1,0]
	v_pk_mul_f32 v[40:41], v[0:1], v[40:41]
	v_pk_mul_f32 v[42:43], v[2:3], v[42:43]
	v_pk_mul_f32 v[44:45], v[4:5], v[44:45]
	v_pk_mul_f32 v[46:47], v[6:7], v[46:47]
	v_pk_mul_f32 v[48:49], v[8:9], v[48:49]
	v_pk_mul_f32 v[50:51], v[10:11], v[50:51]
	v_pk_mul_f32 v[52:53], v[12:13], v[52:53]
	v_pk_mul_f32 v[54:55], v[14:15], v[54:55]
	v_pk_fma_f32 v[40:41], v[56:57], v[40:41], v[72:73]
	v_pk_fma_f32 v[42:43], v[58:59], v[42:43], v[74:75]
	v_pk_fma_f32 v[44:45], v[60:61], v[44:45], v[76:77]
	v_pk_fma_f32 v[46:47], v[62:63], v[46:47], v[78:79]
	v_pk_fma_f32 v[48:49], v[64:65], v[48:49], v[80:81]
	v_pk_fma_f32 v[50:51], v[66:67], v[50:51], v[82:83]
	v_pk_fma_f32 v[52:53], v[68:69], v[52:53], v[84:85]
	v_pk_fma_f32 v[54:55], v[70:71], v[54:55], v[86:87]
	v_cvt_pk_bf16_f32 v32, v40, v41
	v_cvt_pk_bf16_f32 v33, v42, v43
	v_cvt_pk_bf16_f32 v34, v44, v45
	v_cvt_pk_bf16_f32 v35, v46, v47
	v_cvt_pk_bf16_f32 v36, v48, v49
	v_cvt_pk_bf16_f32 v37, v50, v51
	v_cvt_pk_bf16_f32 v38, v52, v53
	v_cvt_pk_bf16_f32 v39, v54, v55
	s_lshl_b32 s12, s6, 11
	s_add_u32 s6, s24, s12
	s_addc_u32 s7, s25, 0
	global_store_dwordx2 v17, v[32:33], s[6:7]
	global_store_dwordx2 v17, v[34:35], s[6:7] offset:512
	global_store_dwordx2 v17, v[36:37], s[6:7] offset:1024
	global_store_dwordx2 v17, v[38:39], s[6:7] offset:1536
	s_add_u32 s3, s3, 1
	s_sub_u32 s7, s8, 1
	s_min_u32 s6, s3, s7
	s_lshr_b32 s12, s6, 13
	s_min_u32 s12, s12, 8
	s_cmp_eq_u32 s12, s9
	s_cbranch_scc1 .Lrn3_nomod1
; DI unsigned pk2(float lo, float hi) { const f32x2 v = {lo, hi}; return __builtin_bit_cast(unsigned, __builtin_convertvector(v, bf16x2v)); }
; DI void rownorm_phase(const float* srcL, const float* srcC, int M, const float* __restrict__ gain, const float* __restrict__ mod, int shift_idx, int scale_idx, bf16_t* __restrict__ H) {
;     ...
;         f32x4 v[4]; float ss = 0.f;
; #pragma unroll
;         for (int i = 0; i < 4; ++i) { v[i] = __builtin_nontemporal_load((const f32x4*)(src + (i * 64 + lane) * 4)); ss += v[i].x * v[i].x + v[i].y * v[i].y + v[i].z * v[i].z + v[i].w * v[i].w; }
; #pragma unroll
;         for (int o = 32; o > 0; o >>= 1) ss += __shfl_xor(ss, o);
;         const float rs = rsqrtf(ss * (1.0f / 1024.0f) + EPS);
; #pragma unroll
;         for (int i = 0; i < 4; ++i) {
;             const int col = (i * 64 + lane) * 4;
;             const f32x4 g = *(const f32x4*)(gain + col), sc = *(const f32x4*)(mrow + scale_idx * 1024 + col), sh = *(const f32x4*)(mrow + shift_idx * 1024 + col);
;             const f32x4 y = (v[i] * rs * g) * (sc + 1.0f) + sh;
;             u32x2 o; o.x = pk2(y.x, y.y); o.y = pk2(y.z, y.w);
;             *(u32x2*)(H + (size_t)row * DM + col) = o;
;         }
;     }
	s_mov_b32 s9, s12
	s_mul_i32 s12, s12, 0x6000
	s_add_u32 s4, s28, s12
	s_addc_u32 s5, s29, 0
	s_add_u32 s4, s4, 0x1000
	s_addc_u32 s5, s5, 0
	global_load_dwordx4 v[56:59], v16, s[4:5]
	global_load_dwordx4 v[60:63], v16, s[4:5] offset:1024
	global_load_dwordx4 v[64:67], v16, s[4:5] offset:2048
	global_load_dwordx4 v[68:71], v16, s[4:5] offset:3072
	s_sub_u32 s4, s4, 0x1000
	s_subb_u32 s5, s5, 0
	global_load_dwordx4 v[72:75], v16, s[4:5]
	global_load_dwordx4 v[76:79], v16, s[4:5] offset:1024
	global_load_dwordx4 v[80:83], v16, s[4:5] offset:2048
	global_load_dwordx4 v[84:87], v16, s[4:5] offset:3072
	s_waitcnt vmcnt(4)
	v_pk_add_f32 v[56:57], v[56:57], 1.0 op_sel_hi:[1,0]
	v_pk_add_f32 v[58:59], v[58:59], 1.0 op_sel_hi:[1,0]
	v_pk_add_f32 v[60:61], v[60:61], 1.0 op_sel_hi:[1,0]
	v_pk_add_f32 v[62:63], v[62:63], 1.0 op_sel_hi:[1,0]
	v_pk_add_f32 v[64:65], v[64:65], 1.0 op_sel_hi:[1,0]
	v_pk_add_f32 v[66:67], v[66:67], 1.0 op_sel_hi:[1,0]
	v_pk_add_f32 v[68:69], v[68:69], 1.0 op_sel_hi:[1,0]
	v_pk_add_f32 v[70:71], v[70:71], 1.0 op_sel_hi:[1,0]
	s_waitcnt vmcnt(0)
.Lrn3_nomod1:
	s_waitcnt vmcnt(4)
	s_add_u32 s12, s3, 2
	s_min_u32 s7, s12, s7
	s_cmp_lt_u32 s7, 0x10000
	s_cselect_b32 s12, s48, s26
	s_cselect_b32 s13, s49, s27
	s_and_b32 s4, s7, 0xffff
	s_lshr_b32 s5, s4, 20
	s_lshl_b32 s4, s4, 12
	s_add_u32 s4, s4, s12
	s_addc_u32 s5, s5, s13
	global_load_dwordx4 v[40:43], v16, s[4:5]
	global_load_dwordx4 v[44:47], v16, s[4:5] offset:1024
	global_load_dwordx4 v[48:51], v16, s[4:5] offset:2048
	global_load_dwordx4 v[52:55], v16, s[4:5] offset:3072
	v_mul_f32_e32 v20, v89, v89
	v_fmac_f32_e32 v20, v88, v88
	v_fmac_f32_e32 v20, v90, v90
	v_fmac_f32_e32 v20, v91, v91
	v_mul_f32_e32 v21, v93, v93
	v_fmac_f32_e32 v21, v92, v92
	v_fmac_f32_e32 v21, v94, v94
	v_fmac_f32_e32 v21, v95, v95
	v_mul_f32_e32 v22, v97, v97
	v_fmac_f32_e32 v22, v96, v96
	v_fmac_f32_e32 v22, v98, v98
	v_fmac_f32_e32 v22, v99, v99
	v_mul_f32_e32 v23, v101, v101
	v_fmac_f32_e32 v23, v100, v100
	v_fmac_f32_e32 v23, v102, v102
	v_fmac_f32_e32 v23, v103, v103
	v_add_f32_e32 v28, v20, v21
	v_add_f32_e32 v28, v28, v22
	v_add_f32_e32 v28, v28, v23
	s_nop 1
	v_add_f32_dpp v28, v28, v28 quad_perm:[1,0,3,2] row_mask:0xf bank_mask:0xf
	s_nop 1
	v_add_f32_dpp v28, v28, v28 quad_perm:[2,3,0,1] row_mask:0xf bank_mask:0xf
	s_nop 1
	v_add_f32_dpp v28, v28, v28 row_half_mirror row_mask:0xf bank_mask:0xf
	s_nop 1
	v_add_f32_dpp v28, v28, v28 row_mirror row_mask:0xf bank_mask:0xf
	s_nop 1
	v_readlane_b32 s4, v28, 0
	v_readlane_b32 s5, v28, 16
	v_readlane_b32 s12, v28, 32
	v_readlane_b32 s13, v28, 48
	s_nop 1
	v_mov_b32_e32 v29, s4
	v_add_f32_e32 v29, s5, v29
	v_add_f32_e32 v29, s12, v29
	v_add_f32_e32 v29, s13, v29
	v_fmamk_f32 v29, v29, 0x3a800000, v30
	v_mul_f32_e32 v31, 0x4b800000, v29
	v_cmp_gt_f32_e32 vcc, 0x800000, v29
	s_nop 1
	v_cndmask_b32_e32 v29, v29, v31, vcc
	v_rsq_f32_e32 v29, v29
	s_nop 1
	v_mul_f32_e32 v31, 0x45800000, v29
	v_cndmask_b32_e32 v18, v29, v31, vcc
	s_nop 0
	v_pk_mul_f32 v[88:89], v[88:89], v[18:19] op_sel_hi:[1,0]
	v_pk_mul_f32 v[90:91], v[90:91], v[18:19] op_sel_hi:[1,0]
	v_pk_mul_f32 v[92:93], v[92:93], v[18:19] op_sel_hi:[1,0]
	v_pk_mul_f32 v[94:95], v[94:95], v[18:19] op_sel_hi:[1,0]
	v_pk_mul_f32 v[96:97], v[96:97], v[18:19] op_sel_hi:[1,0]
	v_pk_mul_f32 v[98:99], v[98:99], v[18:19] op_sel_hi:[1,0]
	v_pk_mul_f32 v[100:101], v[100:101], v[18:19] op_sel_hi:[1,0]
	v_pk_mul_f32 v[102:103], v[102:103], v[18:19] op_sel_hi:[1,0]
	v_pk_mul_f32 v[88:89], v[0:1], v[88:89]
	v_pk_mul_f32 v[90:91], v[2:3], v[90:91]
	v_pk_mul_f32 v[92:93], v[4:5], v[92:93]
	v_pk_mul_f32 v[94:95], v[6:7], v[94:95]
	v_pk_mul_f32 v[96:97], v[8:9], v[96:97]
	v_pk_mul_f32 v[98:99], v[10:11], v[98:99]
	v_pk_mul_f32 v[100:101], v[12:13], v[100:101]
	v_pk_mul_f32 v[102:103], v[14:15], v[102:103]
	v_pk_fma_f32 v[88:89], v[56:57], v[88:89], v[72:73]
	v_pk_fma_f32 v[90:91], v[58:59], v[90:91], v[74:75]
	v_pk_fma_f32 v[92:93], v[60:61], v[92:93], v[76:77]
	v_pk_fma_f32 v[94:95], v[62:63], v[94:95], v[78:79]
	v_pk_fma_f32 v[96:97], v[64:65], v[96:97], v[80:81]
	v_pk_fma_f32 v[98:99], v[66:67], v[98:99], v[82:83]
	v_pk_fma_f32 v[100:101], v[68:69], v[100:101], v[84:85]
	v_pk_fma_f32 v[102:103], v[70:71], v[102:103], v[86:87]
	v_cvt_pk_bf16_f32 v32, v88, v89
	v_cvt_pk_bf16_f32 v33, v90, v91
	v_cvt_pk_bf16_f32 v34, v92, v93
	v_cvt_pk_bf16_f32 v35, v94, v95
	v_cvt_pk_bf16_f32 v36, v96, v97
	v_cvt_pk_bf16_f32 v37, v98, v99
	v_cvt_pk_bf16_f32 v38, v100, v101
	v_cvt_pk_bf16_f32 v39, v102, v103
	s_lshl_b32 s12, s6, 11
	s_add_u32 s6, s24, s12
	s_addc_u32 s7, s25, 0
	global_store_dwordx2 v17, v[32:33], s[6:7]
	global_store_dwordx2 v17, v[34:35], s[6:7] offset:512
	global_store_dwordx2 v17, v[36:37], s[6:7] offset:1024
	global_store_dwordx2 v17, v[38:39], s[6:7] offset:1536
	s_add_u32 s3, s3, 1
	s_sub_u32 s7, s8, 1
	s_min_u32 s6, s3, s7
	s_lshr_b32 s12, s6, 13
	s_min_u32 s12, s12, 8
	s_cmp_eq_u32 s12, s9
	s_cbranch_scc1 .Lrn3_nomod2
	s_mov_b32 s9, s12
	s_mul_i32 s12, s12, 0x6000
	s_add_u32 s4, s28, s12
	s_addc_u32 s5, s29, 0
	s_add_u32 s4, s4, 0x1000
	s_addc_u32 s5, s5, 0
	global_load_dwordx4 v[56:59], v16, s[4:5]
	global_load_dwordx4 v[60:63], v16, s[4:5] offset:1024
	global_load_dwordx4 v[64:67], v16, s[4:5] offset:2048
	global_load_dwordx4 v[68:71], v16, s[4:5] offset:3072
	s_sub_u32 s4, s4, 0x1000
	s_subb_u32 s5, s5, 0
	global_load_dwordx4 v[72:75], v16, s[4:5]
	global_load_dwordx4 v[76:79], v16, s[4:5] offset:1024
	global_load_dwordx4 v[80:83], v16, s[4:5] offset:2048
	global_load_dwordx4 v[84:87], v16, s[4:5] offset:3072
	s_waitcnt vmcnt(4)
	v_pk_add_f32 v[56:57], v[56:57], 1.0 op_sel_hi:[1,0]
	v_pk_add_f32 v[58:59], v[58:59], 1.0 op_sel_hi:[1,0]
	v_pk_add_f32 v[60:61], v[60:61], 1.0 op_sel_hi:[1,0]
	v_pk_add_f32 v[62:63], v[62:63], 1.0 op_sel_hi:[1,0]
	v_pk_add_f32 v[64:65], v[64:65], 1.0 op_sel_hi:[1,0]
	v_pk_add_f32 v[66:67], v[66:67], 1.0 op_sel_hi:[1,0]
	v_pk_add_f32 v[68:69], v[68:69], 1.0 op_sel_hi:[1,0]
	v_pk_add_f32 v[70:71], v[70:71], 1.0 op_sel_hi:[1,0]
	s_waitcnt vmcnt(0)
; DI unsigned pk2(float lo, float hi) { const f32x2 v = {lo, hi}; return __builtin_bit_cast(unsigned, __builtin_convertvector(v, bf16x2v)); }
; DI void rownorm_phase(const float* srcL, const float* srcC, int M, const float* __restrict__ gain, const float* __restrict__ mod, int shift_idx, int scale_idx, bf16_t* __restrict__ H) {
;     ...
;         f32x4 v[4]; float ss = 0.f;
; #pragma unroll
;         for (int i = 0; i < 4; ++i) { v[i] = __builtin_nontemporal_load((const f32x4*)(src + (i * 64 + lane) * 4)); ss += v[i].x * v[i].x + v[i].y * v[i].y + v[i].z * v[i].z + v[i].w * v[i].w; }
; #pragma unroll
;         for (int o = 32; o > 0; o >>= 1) ss += __shfl_xor(ss, o);
;         const float rs = rsqrtf(ss * (1.0f / 1024.0f) + EPS);
; #pragma unroll
;         for (int i = 0; i < 4; ++i) {
;             const int col = (i * 64 + lane) * 4;
;             const f32x4 g = *(const f32x4*)(gain + col), sc = *(const f32x4*)(mrow + scale_idx * 1024 + col), sh = *(const f32x4*)(mrow + shift_idx * 1024 + col);
;             const f32x4 y = (v[i] * rs * g) * (sc + 1.0f) + sh;
;             u32x2 o; o.x = pk2(y.x, y.y); o.y = pk2(y.z, y.w);
;             *(u32x2*)(H + (size_t)row * DM + col) = o;
;         }
;     }
.Lrn3_nomod2:
	s_waitcnt vmcnt(4)
	s_add_u32 s12, s3, 2
	s_min_u32 s7, s12, s7
	s_cmp_lt_u32 s7, 0x10000
	s_cselect_b32 s12, s48, s26
	s_cselect_b32 s13, s49, s27
	s_and_b32 s4, s7, 0xffff
	s_lshr_b32 s5, s4, 20
	s_lshl_b32 s4, s4, 12
	s_add_u32 s4, s4, s12
	s_addc_u32 s5, s5, s13
	global_load_dwordx4 v[88:91], v16, s[4:5]
	global_load_dwordx4 v[92:95], v16, s[4:5] offset:1024
	global_load_dwordx4 v[96:99], v16, s[4:5] offset:2048
	global_load_dwordx4 v[100:103], v16, s[4:5] offset:3072
	v_mul_f32_e32 v20, v105, v105
	v_fmac_f32_e32 v20, v104, v104
	v_fmac_f32_e32 v20, v106, v106
	v_fmac_f32_e32 v20, v107, v107
	v_mul_f32_e32 v21, v109, v109
	v_fmac_f32_e32 v21, v108, v108
	v_fmac_f32_e32 v21, v110, v110
	v_fmac_f32_e32 v21, v111, v111
	v_mul_f32_e32 v22, v113, v113
	v_fmac_f32_e32 v22, v112, v112
	v_fmac_f32_e32 v22, v114, v114
	v_fmac_f32_e32 v22, v115, v115
	v_mul_f32_e32 v23, v117, v117
	v_fmac_f32_e32 v23, v116, v116
	v_fmac_f32_e32 v23, v118, v118
	v_fmac_f32_e32 v23, v119, v119
	v_add_f32_e32 v28, v20, v21
	v_add_f32_e32 v28, v28, v22
	v_add_f32_e32 v28, v28, v23
	s_nop 1
	v_add_f32_dpp v28, v28, v28 quad_perm:[1,0,3,2] row_mask:0xf bank_mask:0xf
	s_nop 1
	v_add_f32_dpp v28, v28, v28 quad_perm:[2,3,0,1] row_mask:0xf bank_mask:0xf
	s_nop 1
	v_add_f32_dpp v28, v28, v28 row_half_mirror row_mask:0xf bank_mask:0xf
	s_nop 1
	v_add_f32_dpp v28, v28, v28 row_mirror row_mask:0xf bank_mask:0xf
	s_nop 1
	v_readlane_b32 s4, v28, 0
	v_readlane_b32 s5, v28, 16
	v_readlane_b32 s12, v28, 32
	v_readlane_b32 s13, v28, 48
	s_nop 1
	v_mov_b32_e32 v29, s4
	v_add_f32_e32 v29, s5, v29
	v_add_f32_e32 v29, s12, v29
	v_add_f32_e32 v29, s13, v29
	v_fmamk_f32 v29, v29, 0x3a800000, v30
	v_mul_f32_e32 v31, 0x4b800000, v29
	v_cmp_gt_f32_e32 vcc, 0x800000, v29
	s_nop 1
	v_cndmask_b32_e32 v29, v29, v31, vcc
	v_rsq_f32_e32 v29, v29
	s_nop 1
	v_mul_f32_e32 v31, 0x45800000, v29
	v_cndmask_b32_e32 v18, v29, v31, vcc
	s_nop 0
	v_pk_mul_f32 v[104:105], v[104:105], v[18:19] op_sel_hi:[1,0]
	v_pk_mul_f32 v[106:107], v[106:107], v[18:19] op_sel_hi:[1,0]
	v_pk_mul_f32 v[108:109], v[108:109], v[18:19] op_sel_hi:[1,0]
	v_pk_mul_f32 v[110:111], v[110:111], v[18:19] op_sel_hi:[1,0]
	v_pk_mul_f32 v[112:113], v[112:113], v[18:19] op_sel_hi:[1,0]
	v_pk_mul_f32 v[114:115], v[114:115], v[18:19] op_sel_hi:[1,0]
	v_pk_mul_f32 v[116:117], v[116:117], v[18:19] op_sel_hi:[1,0]
	v_pk_mul_f32 v[118:119], v[118:119], v[18:19] op_sel_hi:[1,0]
	v_pk_mul_f32 v[104:105], v[0:1], v[104:105]
	v_pk_mul_f32 v[106:107], v[2:3], v[106:107]
	v_pk_mul_f32 v[108:109], v[4:5], v[108:109]
	v_pk_mul_f32 v[110:111], v[6:7], v[110:111]
	v_pk_mul_f32 v[112:113], v[8:9], v[112:113]
	v_pk_mul_f32 v[114:115], v[10:11], v[114:115]
	v_pk_mul_f32 v[116:117], v[12:13], v[116:117]
	v_pk_mul_f32 v[118:119], v[14:15], v[118:119]
	v_pk_fma_f32 v[104:105], v[56:57], v[104:105], v[72:73]
	v_pk_fma_f32 v[106:107], v[58:59], v[106:107], v[74:75]
	v_pk_fma_f32 v[108:109], v[60:61], v[108:109], v[76:77]
	v_pk_fma_f32 v[110:111], v[62:63], v[110:111], v[78:79]
	v_pk_fma_f32 v[112:113], v[64:65], v[112:113], v[80:81]
	v_pk_fma_f32 v[114:115], v[66:67], v[114:115], v[82:83]
	v_pk_fma_f32 v[116:117], v[68:69], v[116:117], v[84:85]
	v_pk_fma_f32 v[118:119], v[70:71], v[118:119], v[86:87]
	v_cvt_pk_bf16_f32 v32, v104, v105
	v_cvt_pk_bf16_f32 v33, v106, v107
	v_cvt_pk_bf16_f32 v34, v108, v109
	v_cvt_pk_bf16_f32 v35, v110, v111
	v_cvt_pk_bf16_f32 v36, v112, v113
	v_cvt_pk_bf16_f32 v37, v114, v115
	v_cvt_pk_bf16_f32 v38, v116, v117
	v_cvt_pk_bf16_f32 v39, v118, v119
	s_lshl_b32 s12, s6, 11
	s_add_u32 s6, s24, s12
	s_addc_u32 s7, s25, 0
	global_store_dwordx2 v17, v[32:33], s[6:7]
	global_store_dwordx2 v17, v[34:35], s[6:7] offset:512
	global_store_dwordx2 v17, v[36:37], s[6:7] offset:1024
	global_store_dwordx2 v17, v[38:39], s[6:7] offset:1536
	s_add_u32 s3, s3, 1
	s_cmp_lt_u32 s3, s8
	s_cbranch_scc1 .Lrn3_loop

; DI unsigned pk2(float lo, float hi) { const f32x2 v = {lo, hi}; return __builtin_bit_cast(unsigned, __builtin_convertvector(v, bf16x2v)); }
; DI int otid() { int t = threadIdx.x; asm volatile("" : "+v"(t)); return t; }
; DI void rownorm_phase(const float* srcL, const float* srcC, int M, const float* __restrict__ gain, const float* __restrict__ mod, int shift_idx, int scale_idx, bf16_t* __restrict__ H) {
;     const int lane = otid() & 63, wave = otid() >> 6;
;     for (int row = blockIdx.x * 4 + wave; row < M; row += gridDim.x * 4) {
;         const bool lat = row < NLAT;
;         const float* src = lat ? srcL + (size_t)row * DM : srcC + (size_t)(row - NLAT) * DM;
;         const float* mrow = mod + (lat ? (row >> 13) : 8) * 6144;
;         f32x4 v[4]; float ss = 0.f;
; #pragma unroll
;         for (int i = 0; i < 4; ++i) { v[i] = __builtin_nontemporal_load((const f32x4*)(src + (i * 64 + lane) * 4)); ss += v[i].x * v[i].x + v[i].y * v[i].y + v[i].z * v[i].z + v[i].w * v[i].w; }
; #pragma unroll
;         for (int o = 32; o > 0; o >>= 1) ss += __shfl_xor(ss, o);
;         const float rs = rsqrtf(ss * (1.0f / 1024.0f) + EPS);
; #pragma unroll
;         for (int i = 0; i < 4; ++i) {
;             const int col = (i * 64 + lane) * 4;
;             const f32x4 g = *(const f32x4*)(gain + col), sc = *(const f32x4*)(mrow + scale_idx * 1024 + col), sh = *(const f32x4*)(mrow + shift_idx * 1024 + col);
;             const f32x4 y = (v[i] * rs * g) * (sc + 1.0f) + sh;
;             u32x2 o; o.x = pk2(y.x, y.y); o.y = pk2(y.z, y.w);
;             *(u32x2*)(H + (size_t)row * DM + col) = o;
;         }
;     }
.LBB0_1295:
	s_or_b64 exec, exec, s[4:5]
	v_mov_b32_e32 v0, v216
	v_mov_b32_e32 v1, v216
	s_barrier
	v_readlane_b32 s3, v251, 38
	v_ashrrev_i32_e32 v1, 6, v1
	s_nop 0
	v_add_u32_e32 v16, s3, v1
	s_mov_b32 s3, 0x10000
	v_cmp_gt_i32_e32 vcc, s3, v16
	s_and_saveexec_b64 s[4:5], vcc
	s_cbranch_execz .LBB0_1298
	s_cmpk_eq_i32 s33, 0x200
	s_cbranch_scc1 .Lrn4_fast
	v_lshlrev_b32_e32 v0, 2, v0
	v_and_b32_e32 v24, 0xfc, v0
	s_add_u32 s6, s76, 0x3000
	v_or_b32_e32 v26, 0x100, v24
	v_or_b32_e32 v28, 0x200, v24
	s_addc_u32 s7, s77, 0
	v_lshlrev_b32_e32 v18, 2, v24
	s_waitcnt vmcnt(3)
	v_or_b32_e32 v38, 0x300, v24
	v_lshlrev_b32_e32 v8, 2, v26
	v_lshlrev_b32_e32 v9, 2, v28
	global_load_dwordx4 v[0:3], v8, s[6:7]
	global_load_dwordx4 v[4:7], v9, s[6:7]
	v_lshlrev_b32_e32 v17, 2, v38
	global_load_dwordx4 v[8:11], v18, s[6:7]
	global_load_dwordx4 v[12:15], v17, s[6:7]
	v_mbcnt_hi_u32_b32 v17, -1, v217
	v_and_b32_e32 v19, 64, v17
	v_add_u32_e32 v20, 64, v19
	v_xor_b32_e32 v21, 32, v17
	v_cmp_lt_i32_e32 vcc, v21, v20
	v_mov_b32_e32 v19, 0
	s_mov_b64 s[6:7], 0x3000
	v_cndmask_b32_e32 v21, v17, v21, vcc
	v_lshlrev_b32_e32 v30, 2, v21
	v_xor_b32_e32 v21, 16, v17
	v_cmp_lt_i32_e32 vcc, v21, v20
	s_lshl_b32 s3, s33, 2
	s_mov_b64 s[8:9], 0
	v_cndmask_b32_e32 v21, v17, v21, vcc
	v_lshlrev_b32_e32 v31, 2, v21
	v_xor_b32_e32 v21, 8, v17
	v_cmp_lt_i32_e32 vcc, v21, v20
	v_mov_b32_e32 v36, 0x358637bd
	s_mov_b32 s12, 0x800000
	v_cndmask_b32_e32 v21, v17, v21, vcc
	v_lshlrev_b32_e32 v32, 2, v21
	v_xor_b32_e32 v21, 4, v17
	v_cmp_lt_i32_e32 vcc, v21, v20
	s_mov_b64 s[10:11], 0x4000
	v_mov_b32_e32 v25, v19
	v_cndmask_b32_e32 v21, v17, v21, vcc
	v_lshlrev_b32_e32 v33, 2, v21
	v_xor_b32_e32 v21, 2, v17
	v_cmp_lt_i32_e32 vcc, v21, v20
	v_mov_b32_e32 v27, v19
	v_mov_b32_e32 v29, v19
	v_cndmask_b32_e32 v21, v17, v21, vcc
	v_lshlrev_b32_e32 v34, 2, v21
	v_xor_b32_e32 v21, 1, v17
	v_cmp_lt_i32_e32 vcc, v21, v20
	s_mov_b32 s13, 0xffff
	s_nop 0
	v_cndmask_b32_e32 v17, v17, v21, vcc
	v_lshl_add_u64 v[20:21], s[48:49], 0, v[18:19]
	v_lshlrev_b32_e32 v18, 1, v24
	v_lshlrev_b32_e32 v35, 2, v17
	v_lshl_add_u64 v[22:23], s[24:25], 0, v[18:19]
	v_lshlrev_b32_e32 v18, 2, v24
	v_lshlrev_b32_e32 v24, 2, v26
	v_lshlrev_b32_e32 v26, 2, v28
	v_lshlrev_b32_e32 v28, 2, v38
.LBB0_1297:
	v_ashrrev_i32_e32 v17, 31, v16
	v_lshlrev_b64 v[38:39], 12, v[16:17]
	s_waitcnt vmcnt(6)
	v_lshl_add_u64 v[54:55], v[20:21], 0, v[38:39]
	global_load_dwordx4 v[38:41], v[54:55], off nt
	global_load_dwordx4 v[42:45], v[54:55], off offset:1024 nt
	global_load_dwordx4 v[46:49], v[54:55], off offset:2048 nt
	global_load_dwordx4 v[50:53], v[54:55], off offset:3072 nt
	v_ashrrev_i32_e32 v37, 13, v16
	v_mul_i32_i24_e32 v54, 0x1800, v37
	v_ashrrev_i32_e32 v55, 31, v54
	s_waitcnt vmcnt(9)
	v_lshl_add_u64 v[70:71], v[54:55], 2, s[28:29]
	v_lshl_add_u64 v[66:67], v[70:71], 0, s[10:11]
	v_lshl_add_u64 v[54:55], v[66:67], 0, v[18:19]
	global_load_dwordx4 v[54:57], v[54:55], off
	v_lshl_add_u64 v[58:59], v[66:67], 0, v[24:25]
	v_lshl_add_u64 v[62:63], v[66:67], 0, v[26:27]
	v_lshl_add_u64 v[66:67], v[66:67], 0, v[28:29]
	v_lshl_add_u64 v[70:71], v[70:71], 0, s[6:7]
	global_load_dwordx4 v[58:61], v[58:59], off
	v_lshl_add_u64 v[86:87], v[70:71], 0, v[18:19]
	global_load_dwordx4 v[62:65], v[62:63], off
	v_lshl_add_u64 v[88:89], v[70:71], 0, v[24:25]
	global_load_dwordx4 v[66:69], v[66:67], off
	v_lshl_add_u64 v[90:91], v[70:71], 0, v[26:27]
	v_lshl_add_u64 v[92:93], v[70:71], 0, v[28:29]
	global_load_dwordx4 v[70:73], v[86:87], off
	global_load_dwordx4 v[74:77], v[88:89], off
	global_load_dwordx4 v[78:81], v[90:91], off
	global_load_dwordx4 v[82:85], v[92:93], off
	s_waitcnt vmcnt(11)
	v_mov_b32_e32 v88, v39
	s_waitcnt vmcnt(10)
	v_mov_b32_e32 v89, v43
	v_mov_b32_e32 v86, v38
	v_mov_b32_e32 v87, v42
	s_waitcnt vmcnt(9)
	v_mov_b32_e32 v96, v47
	s_waitcnt vmcnt(8)
	v_mov_b32_e32 v97, v51
	v_pk_mul_f32 v[88:89], v[88:89], v[88:89]
	v_mov_b32_e32 v90, v40
	v_mov_b32_e32 v91, v44
	v_mov_b32_e32 v94, v46
	v_mov_b32_e32 v95, v50
	v_pk_mul_f32 v[96:97], v[96:97], v[96:97]
	v_pk_fma_f32 v[86:87], v[86:87], v[86:87], v[88:89]
	v_mov_b32_e32 v92, v41
	v_mov_b32_e32 v93, v45
	v_mov_b32_e32 v98, v48
	v_mov_b32_e32 v99, v52
	v_pk_fma_f32 v[88:89], v[94:95], v[94:95], v[96:97]
	v_pk_fma_f32 v[86:87], v[90:91], v[90:91], v[86:87]
	v_mov_b32_e32 v100, v49
	v_mov_b32_e32 v101, v53
	v_pk_fma_f32 v[88:89], v[98:99], v[98:99], v[88:89]
	v_pk_fma_f32 v[86:87], v[92:93], v[92:93], v[86:87]
	v_pk_fma_f32 v[88:89], v[100:101], v[100:101], v[88:89]
	v_add_f32_e32 v37, v86, v87
	v_add_f32_e32 v37, v37, v88
	v_add_f32_e32 v37, v37, v89
	ds_bpermute_b32 v86, v30, v37
	s_waitcnt vmcnt(7)
	v_pk_add_f32 v[56:57], v[56:57], 1.0 op_sel_hi:[1,0]
	v_pk_add_f32 v[54:55], v[54:55], 1.0 op_sel_hi:[1,0]
	s_waitcnt vmcnt(6)
	v_pk_add_f32 v[60:61], v[60:61], 1.0 op_sel_hi:[1,0]
	v_pk_add_f32 v[58:59], v[58:59], 1.0 op_sel_hi:[1,0]
	s_waitcnt lgkmcnt(0)
	v_add_f32_e32 v37, v37, v86
	ds_bpermute_b32 v86, v31, v37
	s_waitcnt vmcnt(5)
	v_pk_add_f32 v[64:65], v[64:65], 1.0 op_sel_hi:[1,0]
	v_pk_add_f32 v[62:63], v[62:63], 1.0 op_sel_hi:[1,0]
	s_waitcnt vmcnt(4)
	v_pk_add_f32 v[68:69], v[68:69], 1.0 op_sel_hi:[1,0]
	v_pk_add_f32 v[66:67], v[66:67], 1.0 op_sel_hi:[1,0]
	s_waitcnt lgkmcnt(0)
	v_add_f32_e32 v37, v37, v86
	ds_bpermute_b32 v86, v32, v37
	s_waitcnt lgkmcnt(0)
	v_add_f32_e32 v37, v37, v86
	ds_bpermute_b32 v88, v33, v37
	v_lshlrev_b64 v[86:87], 11, v[16:17]
	v_add_u32_e32 v16, s3, v16
	v_cmp_lt_i32_e32 vcc, s13, v16
	s_or_b64 s[8:9], vcc, s[8:9]
	s_waitcnt lgkmcnt(0)
	v_add_f32_e32 v17, v37, v88
	ds_bpermute_b32 v37, v34, v17
	v_lshl_add_u64 v[86:87], v[22:23], 0, v[86:87]
	s_waitcnt lgkmcnt(0)
; DI unsigned pk2(float lo, float hi) { const f32x2 v = {lo, hi}; return __builtin_bit_cast(unsigned, __builtin_convertvector(v, bf16x2v)); }
; DI void rownorm_phase(const float* srcL, const float* srcC, int M, const float* __restrict__ gain, const float* __restrict__ mod, int shift_idx, int scale_idx, bf16_t* __restrict__ H) {
;     ...
;         f32x4 v[4]; float ss = 0.f;
; #pragma unroll
;         for (int i = 0; i < 4; ++i) { v[i] = __builtin_nontemporal_load((const f32x4*)(src + (i * 64 + lane) * 4)); ss += v[i].x * v[i].x + v[i].y * v[i].y + v[i].z * v[i].z + v[i].w * v[i].w; }
; #pragma unroll
;         for (int o = 32; o > 0; o >>= 1) ss += __shfl_xor(ss, o);
;         const float rs = rsqrtf(ss * (1.0f / 1024.0f) + EPS);
; #pragma unroll
;         for (int i = 0; i < 4; ++i) {
;             const int col = (i * 64 + lane) * 4;
;             const f32x4 g = *(const f32x4*)(gain + col), sc = *(const f32x4*)(mrow + scale_idx * 1024 + col), sh = *(const f32x4*)(mrow + shift_idx * 1024 + col);
;             const f32x4 y = (v[i] * rs * g) * (sc + 1.0f) + sh;
;             u32x2 o; o.x = pk2(y.x, y.y); o.y = pk2(y.z, y.w);
;             *(u32x2*)(H + (size_t)row * DM + col) = o;
;         }
;     }
	v_add_f32_e32 v17, v17, v37
	ds_bpermute_b32 v37, v35, v17
	s_waitcnt lgkmcnt(0)
	v_add_f32_e32 v17, v17, v37
	v_fmamk_f32 v17, v17, 0x3a800000, v36
	v_mul_f32_e32 v37, 0x4b800000, v17
	v_cmp_gt_f32_e32 vcc, s12, v17
	s_nop 1
	v_cndmask_b32_e32 v17, v17, v37, vcc
	v_rsq_f32_e32 v17, v17
	s_nop 0
	v_mul_f32_e32 v37, 0x45800000, v17
	v_cndmask_b32_e32 v88, v17, v37, vcc
	v_pk_mul_f32 v[40:41], v[40:41], v[88:89] op_sel_hi:[1,0]
	v_pk_mul_f32 v[38:39], v[38:39], v[88:89] op_sel_hi:[1,0]
	v_pk_mul_f32 v[44:45], v[44:45], v[88:89] op_sel_hi:[1,0]
	v_pk_mul_f32 v[42:43], v[42:43], v[88:89] op_sel_hi:[1,0]
	v_pk_mul_f32 v[48:49], v[48:49], v[88:89] op_sel_hi:[1,0]
	v_pk_mul_f32 v[46:47], v[46:47], v[88:89] op_sel_hi:[1,0]
	v_pk_mul_f32 v[52:53], v[52:53], v[88:89] op_sel_hi:[1,0]
	v_pk_mul_f32 v[50:51], v[50:51], v[88:89] op_sel_hi:[1,0]
	v_pk_mul_f32 v[38:39], v[8:9], v[38:39]
	v_pk_mul_f32 v[40:41], v[10:11], v[40:41]
	v_pk_mul_f32 v[42:43], v[0:1], v[42:43]
	v_pk_mul_f32 v[44:45], v[2:3], v[44:45]
	v_pk_mul_f32 v[46:47], v[4:5], v[46:47]
	v_pk_mul_f32 v[48:49], v[6:7], v[48:49]
	v_pk_mul_f32 v[50:51], v[12:13], v[50:51]
	v_pk_mul_f32 v[52:53], v[14:15], v[52:53]
	s_waitcnt vmcnt(3)
	v_pk_fma_f32 v[40:41], v[56:57], v[40:41], v[72:73]
	v_pk_fma_f32 v[38:39], v[54:55], v[38:39], v[70:71]
	s_waitcnt vmcnt(2)
	v_pk_fma_f32 v[44:45], v[60:61], v[44:45], v[76:77]
	v_pk_fma_f32 v[42:43], v[58:59], v[42:43], v[74:75]
	s_waitcnt vmcnt(1)
	v_pk_fma_f32 v[48:49], v[64:65], v[48:49], v[80:81]
	v_pk_fma_f32 v[46:47], v[62:63], v[46:47], v[78:79]
	s_waitcnt vmcnt(0)
	v_pk_fma_f32 v[52:53], v[68:69], v[52:53], v[84:85]
	v_pk_fma_f32 v[50:51], v[66:67], v[50:51], v[82:83]
	v_cvt_pk_bf16_f32 v38, v38, v39
	v_cvt_pk_bf16_f32 v39, v40, v41
	v_cvt_pk_bf16_f32 v40, v42, v43
	v_cvt_pk_bf16_f32 v41, v44, v45
	v_cvt_pk_bf16_f32 v42, v46, v47
	v_cvt_pk_bf16_f32 v43, v48, v49
	v_cvt_pk_bf16_f32 v44, v50, v51
	v_cvt_pk_bf16_f32 v45, v52, v53
	global_store_dwordx2 v[86:87], v[38:39], off
	global_store_dwordx2 v[86:87], v[40:41], off offset:512
	global_store_dwordx2 v[86:87], v[42:43], off offset:1024
	global_store_dwordx2 v[86:87], v[44:45], off offset:1536
	s_andn2_b64 exec, exec, s[8:9]
	s_cbranch_execnz .LBB0_1297
	s_branch .LBB0_1298
.Lrn4_fast:
	v_lshrrev_b32_e32 v20, 6, v216
	v_and_b32_e32 v21, 63, v216
	v_mov_b32_e32 v30, 0x358637bd
	v_readfirstlane_b32 s3, v20
	s_lshl_b32 s12, s2, 2
	v_lshlrev_b32_e32 v16, 4, v21
	v_lshlrev_b32_e32 v17, 3, v21
	s_add_u32 s3, s3, s12
	s_mul_i32 s3, s3, 32
	s_add_u32 s10, s3, 32
	s_add_u32 s6, s76, 0x3000
	s_addc_u32 s7, s77, 0
	s_mov_b32 s11, -1
	global_load_dwordx4 v[0:3], v16, s[6:7]
	global_load_dwordx4 v[4:7], v16, s[6:7] offset:1024
	global_load_dwordx4 v[8:11], v16, s[6:7] offset:2048
	global_load_dwordx4 v[12:15], v16, s[6:7] offset:3072
	s_lshr_b32 s7, s3, 20
	s_lshl_b32 s6, s3, 12
	s_add_u32 s6, s6, s48
	s_addc_u32 s7, s7, s49
	global_load_dwordx4 v[40:43], v16, s[6:7]
	global_load_dwordx4 v[44:47], v16, s[6:7] offset:1024
	global_load_dwordx4 v[48:51], v16, s[6:7] offset:2048
	global_load_dwordx4 v[52:55], v16, s[6:7] offset:3072
	s_add_u32 s12, s3, 1
	s_mov_b32 s8, s12
	s_lshr_b32 s7, s8, 20
	s_lshl_b32 s6, s8, 12
	s_add_u32 s6, s6, s48
	s_addc_u32 s7, s7, s49
	global_load_dwordx4 v[88:91], v16, s[6:7]
	global_load_dwordx4 v[92:95], v16, s[6:7] offset:1024
	global_load_dwordx4 v[96:99], v16, s[6:7] offset:2048
	global_load_dwordx4 v[100:103], v16, s[6:7] offset:3072
.Lrn4_loop:
	s_sub_u32 s9, s10, 1
	s_min_u32 s8, s3, s9
	s_lshr_b32 s12, s8, 13
	s_min_u32 s12, s12, 8
	s_cmp_eq_u32 s12, s11
	s_cbranch_scc1 .Lrn4_nomod0
	s_mov_b32 s11, s12
	s_mul_i32 s12, s12, 0x6000
	s_add_u32 s6, s28, s12
	s_addc_u32 s7, s29, 0
	s_add_u32 s6, s6, 0x4000
	s_addc_u32 s7, s7, 0
	global_load_dwordx4 v[56:59], v16, s[6:7]
	global_load_dwordx4 v[60:63], v16, s[6:7] offset:1024
	global_load_dwordx4 v[64:67], v16, s[6:7] offset:2048
	global_load_dwordx4 v[68:71], v16, s[6:7] offset:3072
	s_sub_u32 s6, s6, 0x1000
	s_subb_u32 s7, s7, 0
	global_load_dwordx4 v[72:75], v16, s[6:7]
	global_load_dwordx4 v[76:79], v16, s[6:7] offset:1024
	global_load_dwordx4 v[80:83], v16, s[6:7] offset:2048
	global_load_dwordx4 v[84:87], v16, s[6:7] offset:3072
	s_waitcnt vmcnt(4)
	v_pk_add_f32 v[56:57], v[56:57], 1.0 op_sel_hi:[1,0]
	v_pk_add_f32 v[58:59], v[58:59], 1.0 op_sel_hi:[1,0]
	v_pk_add_f32 v[60:61], v[60:61], 1.0 op_sel_hi:[1,0]
	v_pk_add_f32 v[62:63], v[62:63], 1.0 op_sel_hi:[1,0]
	v_pk_add_f32 v[64:65], v[64:65], 1.0 op_sel_hi:[1,0]
	v_pk_add_f32 v[66:67], v[66:67], 1.0 op_sel_hi:[1,0]
	v_pk_add_f32 v[68:69], v[68:69], 1.0 op_sel_hi:[1,0]
	v_pk_add_f32 v[70:71], v[70:71], 1.0 op_sel_hi:[1,0]
	s_waitcnt vmcnt(0)
; DI unsigned pk2(float lo, float hi) { const f32x2 v = {lo, hi}; return __builtin_bit_cast(unsigned, __builtin_convertvector(v, bf16x2v)); }
; DI void rownorm_phase(const float* srcL, const float* srcC, int M, const float* __restrict__ gain, const float* __restrict__ mod, int shift_idx, int scale_idx, bf16_t* __restrict__ H) {
;     ...
;         f32x4 v[4]; float ss = 0.f;
; #pragma unroll
;         for (int i = 0; i < 4; ++i) { v[i] = __builtin_nontemporal_load((const f32x4*)(src + (i * 64 + lane) * 4)); ss += v[i].x * v[i].x + v[i].y * v[i].y + v[i].z * v[i].z + v[i].w * v[i].w; }
; #pragma unroll
;         for (int o = 32; o > 0; o >>= 1) ss += __shfl_xor(ss, o);
;         const float rs = rsqrtf(ss * (1.0f / 1024.0f) + EPS);
; #pragma unroll
;         for (int i = 0; i < 4; ++i) {
;             const int col = (i * 64 + lane) * 4;
;             const f32x4 g = *(const f32x4*)(gain + col), sc = *(const f32x4*)(mrow + scale_idx * 1024 + col), sh = *(const f32x4*)(mrow + shift_idx * 1024 + col);
;             const f32x4 y = (v[i] * rs * g) * (sc + 1.0f) + sh;
;             u32x2 o; o.x = pk2(y.x, y.y); o.y = pk2(y.z, y.w);
;             *(u32x2*)(H + (size_t)row * DM + col) = o;
;         }
;     }
.Lrn4_nomod0:
	s_waitcnt vmcnt(4)
	s_add_u32 s12, s3, 2
	s_min_u32 s9, s12, s9
	s_lshr_b32 s7, s9, 20
	s_lshl_b32 s6, s9, 12
	s_add_u32 s6, s6, s48
	s_addc_u32 s7, s7, s49
	global_load_dwordx4 v[104:107], v16, s[6:7]
	global_load_dwordx4 v[108:111], v16, s[6:7] offset:1024
	global_load_dwordx4 v[112:115], v16, s[6:7] offset:2048
	global_load_dwordx4 v[116:119], v16, s[6:7] offset:3072
	v_mul_f32_e32 v20, v41, v41
	v_fmac_f32_e32 v20, v40, v40
	v_fmac_f32_e32 v20, v42, v42
	v_fmac_f32_e32 v20, v43, v43
	v_mul_f32_e32 v21, v45, v45
	v_fmac_f32_e32 v21, v44, v44
	v_fmac_f32_e32 v21, v46, v46
	v_fmac_f32_e32 v21, v47, v47
	v_mul_f32_e32 v22, v49, v49
	v_fmac_f32_e32 v22, v48, v48
	v_fmac_f32_e32 v22, v50, v50
	v_fmac_f32_e32 v22, v51, v51
	v_mul_f32_e32 v23, v53, v53
	v_fmac_f32_e32 v23, v52, v52
	v_fmac_f32_e32 v23, v54, v54
	v_fmac_f32_e32 v23, v55, v55
	v_add_f32_e32 v28, v20, v21
	v_add_f32_e32 v28, v28, v22
	v_add_f32_e32 v28, v28, v23
	s_nop 1
	v_add_f32_dpp v28, v28, v28 quad_perm:[1,0,3,2] row_mask:0xf bank_mask:0xf
	s_nop 1
	v_add_f32_dpp v28, v28, v28 quad_perm:[2,3,0,1] row_mask:0xf bank_mask:0xf
	s_nop 1
	v_add_f32_dpp v28, v28, v28 row_half_mirror row_mask:0xf bank_mask:0xf
	s_nop 1
	v_add_f32_dpp v28, v28, v28 row_mirror row_mask:0xf bank_mask:0xf
	s_nop 1
	v_readlane_b32 s6, v28, 0
	v_readlane_b32 s7, v28, 16
	v_readlane_b32 s12, v28, 32
	v_readlane_b32 s13, v28, 48
	s_nop 1
	v_mov_b32_e32 v29, s6
	v_add_f32_e32 v29, s7, v29
	v_add_f32_e32 v29, s12, v29
	v_add_f32_e32 v29, s13, v29
	v_fmamk_f32 v29, v29, 0x3a800000, v30
	v_mul_f32_e32 v31, 0x4b800000, v29
	v_cmp_gt_f32_e32 vcc, 0x800000, v29
	s_nop 1
	v_cndmask_b32_e32 v29, v29, v31, vcc
	v_rsq_f32_e32 v29, v29
	s_nop 1
	v_mul_f32_e32 v31, 0x45800000, v29
	v_cndmask_b32_e32 v18, v29, v31, vcc
	s_nop 0
	v_pk_mul_f32 v[40:41], v[40:41], v[18:19] op_sel_hi:[1,0]
	v_pk_mul_f32 v[42:43], v[42:43], v[18:19] op_sel_hi:[1,0]
	v_pk_mul_f32 v[44:45], v[44:45], v[18:19] op_sel_hi:[1,0]
	v_pk_mul_f32 v[46:47], v[46:47], v[18:19] op_sel_hi:[1,0]
	v_pk_mul_f32 v[48:49], v[48:49], v[18:19] op_sel_hi:[1,0]
	v_pk_mul_f32 v[50:51], v[50:51], v[18:19] op_sel_hi:[1,0]
	v_pk_mul_f32 v[52:53], v[52:53], v[18:19] op_sel_hi:[1,0]
	v_pk_mul_f32 v[54:55], v[54:55], v[18:19] op_sel_hi:[1,0]
	v_pk_mul_f32 v[40:41], v[0:1], v[40:41]
	v_pk_mul_f32 v[42:43], v[2:3], v[42:43]
	v_pk_mul_f32 v[44:45], v[4:5], v[44:45]
	v_pk_mul_f32 v[46:47], v[6:7], v[46:47]
	v_pk_mul_f32 v[48:49], v[8:9], v[48:49]
	v_pk_mul_f32 v[50:51], v[10:11], v[50:51]
	v_pk_mul_f32 v[52:53], v[12:13], v[52:53]
	v_pk_mul_f32 v[54:55], v[14:15], v[54:55]
	v_pk_fma_f32 v[40:41], v[56:57], v[40:41], v[72:73]
	v_pk_fma_f32 v[42:43], v[58:59], v[42:43], v[74:75]
	v_pk_fma_f32 v[44:45], v[60:61], v[44:45], v[76:77]
	v_pk_fma_f32 v[46:47], v[62:63], v[46:47], v[78:79]
	v_pk_fma_f32 v[48:49], v[64:65], v[48:49], v[80:81]
	v_pk_fma_f32 v[50:51], v[66:67], v[50:51], v[82:83]
	v_pk_fma_f32 v[52:53], v[68:69], v[52:53], v[84:85]
	v_pk_fma_f32 v[54:55], v[70:71], v[54:55], v[86:87]
	v_cvt_pk_bf16_f32 v32, v40, v41
	v_cvt_pk_bf16_f32 v33, v42, v43
	v_cvt_pk_bf16_f32 v34, v44, v45
	v_cvt_pk_bf16_f32 v35, v46, v47
	v_cvt_pk_bf16_f32 v36, v48, v49
	v_cvt_pk_bf16_f32 v37, v50, v51
	v_cvt_pk_bf16_f32 v38, v52, v53
	v_cvt_pk_bf16_f32 v39, v54, v55
	s_lshl_b32 s12, s8, 11
	s_add_u32 s8, s24, s12
	s_addc_u32 s9, s25, 0
	global_store_dwordx2 v17, v[32:33], s[8:9]
	global_store_dwordx2 v17, v[34:35], s[8:9] offset:512
	global_store_dwordx2 v17, v[36:37], s[8:9] offset:1024
	global_store_dwordx2 v17, v[38:39], s[8:9] offset:1536
	s_add_u32 s3, s3, 1
	s_sub_u32 s9, s10, 1
	s_min_u32 s8, s3, s9
	s_lshr_b32 s12, s8, 13
	s_min_u32 s12, s12, 8
	s_cmp_eq_u32 s12, s11
	s_cbranch_scc1 .Lrn4_nomod1
	s_mov_b32 s11, s12
	s_mul_i32 s12, s12, 0x6000
	s_add_u32 s6, s28, s12
	s_addc_u32 s7, s29, 0
	s_add_u32 s6, s6, 0x4000
	s_addc_u32 s7, s7, 0
	global_load_dwordx4 v[56:59], v16, s[6:7]
	global_load_dwordx4 v[60:63], v16, s[6:7] offset:1024
	global_load_dwordx4 v[64:67], v16, s[6:7] offset:2048
	global_load_dwordx4 v[68:71], v16, s[6:7] offset:3072
	s_sub_u32 s6, s6, 0x1000
	s_subb_u32 s7, s7, 0
	global_load_dwordx4 v[72:75], v16, s[6:7]
	global_load_dwordx4 v[76:79], v16, s[6:7] offset:1024
	global_load_dwordx4 v[80:83], v16, s[6:7] offset:2048
	global_load_dwordx4 v[84:87], v16, s[6:7] offset:3072
	s_waitcnt vmcnt(4)
	v_pk_add_f32 v[56:57], v[56:57], 1.0 op_sel_hi:[1,0]
	v_pk_add_f32 v[58:59], v[58:59], 1.0 op_sel_hi:[1,0]
	v_pk_add_f32 v[60:61], v[60:61], 1.0 op_sel_hi:[1,0]
	v_pk_add_f32 v[62:63], v[62:63], 1.0 op_sel_hi:[1,0]
	v_pk_add_f32 v[64:65], v[64:65], 1.0 op_sel_hi:[1,0]
	v_pk_add_f32 v[66:67], v[66:67], 1.0 op_sel_hi:[1,0]
	v_pk_add_f32 v[68:69], v[68:69], 1.0 op_sel_hi:[1,0]
	v_pk_add_f32 v[70:71], v[70:71], 1.0 op_sel_hi:[1,0]
	s_waitcnt vmcnt(0)
; DI unsigned pk2(float lo, float hi) { const f32x2 v = {lo, hi}; return __builtin_bit_cast(unsigned, __builtin_convertvector(v, bf16x2v)); }
; DI void rownorm_phase(const float* srcL, const float* srcC, int M, const float* __restrict__ gain, const float* __restrict__ mod, int shift_idx, int scale_idx, bf16_t* __restrict__ H) {
;     ...
;         f32x4 v[4]; float ss = 0.f;
; #pragma unroll
;         for (int i = 0; i < 4; ++i) { v[i] = __builtin_nontemporal_load((const f32x4*)(src + (i * 64 + lane) * 4)); ss += v[i].x * v[i].x + v[i].y * v[i].y + v[i].z * v[i].z + v[i].w * v[i].w; }
; #pragma unroll
;         for (int o = 32; o > 0; o >>= 1) ss += __shfl_xor(ss, o);
;         const float rs = rsqrtf(ss * (1.0f / 1024.0f) + EPS);
; #pragma unroll
;         for (int i = 0; i < 4; ++i) {
;             const int col = (i * 64 + lane) * 4;
;             const f32x4 g = *(const f32x4*)(gain + col), sc = *(const f32x4*)(mrow + scale_idx * 1024 + col), sh = *(const f32x4*)(mrow + shift_idx * 1024 + col);
;             const f32x4 y = (v[i] * rs * g) * (sc + 1.0f) + sh;
;             u32x2 o; o.x = pk2(y.x, y.y); o.y = pk2(y.z, y.w);
;             *(u32x2*)(H + (size_t)row * DM + col) = o;
;         }
;     }
.Lrn4_nomod1:
	s_waitcnt vmcnt(4)
	s_add_u32 s12, s3, 2
	s_min_u32 s9, s12, s9
	s_lshr_b32 s7, s9, 20
	s_lshl_b32 s6, s9, 12
	s_add_u32 s6, s6, s48
	s_addc_u32 s7, s7, s49
	global_load_dwordx4 v[40:43], v16, s[6:7]
	global_load_dwordx4 v[44:47], v16, s[6:7] offset:1024
	global_load_dwordx4 v[48:51], v16, s[6:7] offset:2048
	global_load_dwordx4 v[52:55], v16, s[6:7] offset:3072
	v_mul_f32_e32 v20, v89, v89
	v_fmac_f32_e32 v20, v88, v88
	v_fmac_f32_e32 v20, v90, v90
	v_fmac_f32_e32 v20, v91, v91
	v_mul_f32_e32 v21, v93, v93
	v_fmac_f32_e32 v21, v92, v92
	v_fmac_f32_e32 v21, v94, v94
	v_fmac_f32_e32 v21, v95, v95
	v_mul_f32_e32 v22, v97, v97
	v_fmac_f32_e32 v22, v96, v96
	v_fmac_f32_e32 v22, v98, v98
	v_fmac_f32_e32 v22, v99, v99
	v_mul_f32_e32 v23, v101, v101
	v_fmac_f32_e32 v23, v100, v100
	v_fmac_f32_e32 v23, v102, v102
	v_fmac_f32_e32 v23, v103, v103
	v_add_f32_e32 v28, v20, v21
	v_add_f32_e32 v28, v28, v22
	v_add_f32_e32 v28, v28, v23
	s_nop 1
	v_add_f32_dpp v28, v28, v28 quad_perm:[1,0,3,2] row_mask:0xf bank_mask:0xf
	s_nop 1
	v_add_f32_dpp v28, v28, v28 quad_perm:[2,3,0,1] row_mask:0xf bank_mask:0xf
	s_nop 1
	v_add_f32_dpp v28, v28, v28 row_half_mirror row_mask:0xf bank_mask:0xf
	s_nop 1
	v_add_f32_dpp v28, v28, v28 row_mirror row_mask:0xf bank_mask:0xf
	s_nop 1
	v_readlane_b32 s6, v28, 0
	v_readlane_b32 s7, v28, 16
	v_readlane_b32 s12, v28, 32
	v_readlane_b32 s13, v28, 48
	s_nop 1
	v_mov_b32_e32 v29, s6
	v_add_f32_e32 v29, s7, v29
	v_add_f32_e32 v29, s12, v29
	v_add_f32_e32 v29, s13, v29
	v_fmamk_f32 v29, v29, 0x3a800000, v30
	v_mul_f32_e32 v31, 0x4b800000, v29
	v_cmp_gt_f32_e32 vcc, 0x800000, v29
	s_nop 1
	v_cndmask_b32_e32 v29, v29, v31, vcc
	v_rsq_f32_e32 v29, v29
	s_nop 1
	v_mul_f32_e32 v31, 0x45800000, v29
	v_cndmask_b32_e32 v18, v29, v31, vcc
	s_nop 0
	v_pk_mul_f32 v[88:89], v[88:89], v[18:19] op_sel_hi:[1,0]
	v_pk_mul_f32 v[90:91], v[90:91], v[18:19] op_sel_hi:[1,0]
	v_pk_mul_f32 v[92:93], v[92:93], v[18:19] op_sel_hi:[1,0]
	v_pk_mul_f32 v[94:95], v[94:95], v[18:19] op_sel_hi:[1,0]
	v_pk_mul_f32 v[96:97], v[96:97], v[18:19] op_sel_hi:[1,0]
	v_pk_mul_f32 v[98:99], v[98:99], v[18:19] op_sel_hi:[1,0]
	v_pk_mul_f32 v[100:101], v[100:101], v[18:19] op_sel_hi:[1,0]
	v_pk_mul_f32 v[102:103], v[102:103], v[18:19] op_sel_hi:[1,0]
	v_pk_mul_f32 v[88:89], v[0:1], v[88:89]
	v_pk_mul_f32 v[90:91], v[2:3], v[90:91]
	v_pk_mul_f32 v[92:93], v[4:5], v[92:93]
	v_pk_mul_f32 v[94:95], v[6:7], v[94:95]
	v_pk_mul_f32 v[96:97], v[8:9], v[96:97]
	v_pk_mul_f32 v[98:99], v[10:11], v[98:99]
	v_pk_mul_f32 v[100:101], v[12:13], v[100:101]
	v_pk_mul_f32 v[102:103], v[14:15], v[102:103]
	v_pk_fma_f32 v[88:89], v[56:57], v[88:89], v[72:73]
	v_pk_fma_f32 v[90:91], v[58:59], v[90:91], v[74:75]
	v_pk_fma_f32 v[92:93], v[60:61], v[92:93], v[76:77]
	v_pk_fma_f32 v[94:95], v[62:63], v[94:95], v[78:79]
	v_pk_fma_f32 v[96:97], v[64:65], v[96:97], v[80:81]
	v_pk_fma_f32 v[98:99], v[66:67], v[98:99], v[82:83]
	v_pk_fma_f32 v[100:101], v[68:69], v[100:101], v[84:85]
	v_pk_fma_f32 v[102:103], v[70:71], v[102:103], v[86:87]
	v_cvt_pk_bf16_f32 v32, v88, v89
	v_cvt_pk_bf16_f32 v33, v90, v91
	v_cvt_pk_bf16_f32 v34, v92, v93
	v_cvt_pk_bf16_f32 v35, v94, v95
	v_cvt_pk_bf16_f32 v36, v96, v97
	v_cvt_pk_bf16_f32 v37, v98, v99
	v_cvt_pk_bf16_f32 v38, v100, v101
	v_cvt_pk_bf16_f32 v39, v102, v103
	s_lshl_b32 s12, s8, 11
	s_add_u32 s8, s24, s12
	s_addc_u32 s9, s25, 0
	global_store_dwordx2 v17, v[32:33], s[8:9]
	global_store_dwordx2 v17, v[34:35], s[8:9] offset:512
	global_store_dwordx2 v17, v[36:37], s[8:9] offset:1024
	global_store_dwordx2 v17, v[38:39], s[8:9] offset:1536
	s_add_u32 s3, s3, 1
	s_sub_u32 s9, s10, 1
	s_min_u32 s8, s3, s9
	s_lshr_b32 s12, s8, 13
	s_min_u32 s12, s12, 8
	s_cmp_eq_u32 s12, s11
	s_cbranch_scc1 .Lrn4_nomod2
	s_mov_b32 s11, s12
	s_mul_i32 s12, s12, 0x6000
	s_add_u32 s6, s28, s12
	s_addc_u32 s7, s29, 0
	s_add_u32 s6, s6, 0x4000
	s_addc_u32 s7, s7, 0
	global_load_dwordx4 v[56:59], v16, s[6:7]
	global_load_dwordx4 v[60:63], v16, s[6:7] offset:1024
	global_load_dwordx4 v[64:67], v16, s[6:7] offset:2048
	global_load_dwordx4 v[68:71], v16, s[6:7] offset:3072
	s_sub_u32 s6, s6, 0x1000
	s_subb_u32 s7, s7, 0
	global_load_dwordx4 v[72:75], v16, s[6:7]
	global_load_dwordx4 v[76:79], v16, s[6:7] offset:1024
	global_load_dwordx4 v[80:83], v16, s[6:7] offset:2048
	global_load_dwordx4 v[84:87], v16, s[6:7] offset:3072
	s_waitcnt vmcnt(4)
	v_pk_add_f32 v[56:57], v[56:57], 1.0 op_sel_hi:[1,0]
	v_pk_add_f32 v[58:59], v[58:59], 1.0 op_sel_hi:[1,0]
	v_pk_add_f32 v[60:61], v[60:61], 1.0 op_sel_hi:[1,0]
	v_pk_add_f32 v[62:63], v[62:63], 1.0 op_sel_hi:[1,0]
	v_pk_add_f32 v[64:65], v[64:65], 1.0 op_sel_hi:[1,0]
	v_pk_add_f32 v[66:67], v[66:67], 1.0 op_sel_hi:[1,0]
	v_pk_add_f32 v[68:69], v[68:69], 1.0 op_sel_hi:[1,0]
	v_pk_add_f32 v[70:71], v[70:71], 1.0 op_sel_hi:[1,0]
	s_waitcnt vmcnt(0)
; DI unsigned pk2(float lo, float hi) { const f32x2 v = {lo, hi}; return __builtin_bit_cast(unsigned, __builtin_convertvector(v, bf16x2v)); }
; DI void rownorm_phase(const float* srcL, const float* srcC, int M, const float* __restrict__ gain, const float* __restrict__ mod, int shift_idx, int scale_idx, bf16_t* __restrict__ H) {
;     ...
;         f32x4 v[4]; float ss = 0.f;
; #pragma unroll
;         for (int i = 0; i < 4; ++i) { v[i] = __builtin_nontemporal_load((const f32x4*)(src + (i * 64 + lane) * 4)); ss += v[i].x * v[i].x + v[i].y * v[i].y + v[i].z * v[i].z + v[i].w * v[i].w; }
; #pragma unroll
;         for (int o = 32; o > 0; o >>= 1) ss += __shfl_xor(ss, o);
;         const float rs = rsqrtf(ss * (1.0f / 1024.0f) + EPS);
; #pragma unroll
;         for (int i = 0; i < 4; ++i) {
;             const int col = (i * 64 + lane) * 4;
;             const f32x4 g = *(const f32x4*)(gain + col), sc = *(const f32x4*)(mrow + scale_idx * 1024 + col), sh = *(const f32x4*)(mrow + shift_idx * 1024 + col);
;             const f32x4 y = (v[i] * rs * g) * (sc + 1.0f) + sh;
;             u32x2 o; o.x = pk2(y.x, y.y); o.y = pk2(y.z, y.w);
;             *(u32x2*)(H + (size_t)row * DM + col) = o;
;         }
;     }
.Lrn4_nomod2:
	s_waitcnt vmcnt(4)
	s_add_u32 s12, s3, 2
	s_min_u32 s9, s12, s9
	s_lshr_b32 s7, s9, 20
	s_lshl_b32 s6, s9, 12
	s_add_u32 s6, s6, s48
	s_addc_u32 s7, s7, s49
	global_load_dwordx4 v[88:91], v16, s[6:7]
	global_load_dwordx4 v[92:95], v16, s[6:7] offset:1024
	global_load_dwordx4 v[96:99], v16, s[6:7] offset:2048
	global_load_dwordx4 v[100:103], v16, s[6:7] offset:3072
	v_mul_f32_e32 v20, v105, v105
	v_fmac_f32_e32 v20, v104, v104
	v_fmac_f32_e32 v20, v106, v106
	v_fmac_f32_e32 v20, v107, v107
	v_mul_f32_e32 v21, v109, v109
	v_fmac_f32_e32 v21, v108, v108
	v_fmac_f32_e32 v21, v110, v110
	v_fmac_f32_e32 v21, v111, v111
	v_mul_f32_e32 v22, v113, v113
	v_fmac_f32_e32 v22, v112, v112
	v_fmac_f32_e32 v22, v114, v114
	v_fmac_f32_e32 v22, v115, v115
	v_mul_f32_e32 v23, v117, v117
	v_fmac_f32_e32 v23, v116, v116
	v_fmac_f32_e32 v23, v118, v118
	v_fmac_f32_e32 v23, v119, v119
	v_add_f32_e32 v28, v20, v21
	v_add_f32_e32 v28, v28, v22
	v_add_f32_e32 v28, v28, v23
	s_nop 1
	v_add_f32_dpp v28, v28, v28 quad_perm:[1,0,3,2] row_mask:0xf bank_mask:0xf
	s_nop 1
	v_add_f32_dpp v28, v28, v28 quad_perm:[2,3,0,1] row_mask:0xf bank_mask:0xf
	s_nop 1
	v_add_f32_dpp v28, v28, v28 row_half_mirror row_mask:0xf bank_mask:0xf
	s_nop 1
	v_add_f32_dpp v28, v28, v28 row_mirror row_mask:0xf bank_mask:0xf
	s_nop 1
	v_readlane_b32 s6, v28, 0
	v_readlane_b32 s7, v28, 16
	v_readlane_b32 s12, v28, 32
	v_readlane_b32 s13, v28, 48
	s_nop 1
	v_mov_b32_e32 v29, s6
	v_add_f32_e32 v29, s7, v29
	v_add_f32_e32 v29, s12, v29
	v_add_f32_e32 v29, s13, v29
	v_fmamk_f32 v29, v29, 0x3a800000, v30
	v_mul_f32_e32 v31, 0x4b800000, v29
	v_cmp_gt_f32_e32 vcc, 0x800000, v29
	s_nop 1
	v_cndmask_b32_e32 v29, v29, v31, vcc
	v_rsq_f32_e32 v29, v29
	s_nop 1
	v_mul_f32_e32 v31, 0x45800000, v29
	v_cndmask_b32_e32 v18, v29, v31, vcc
	s_nop 0
	v_pk_mul_f32 v[104:105], v[104:105], v[18:19] op_sel_hi:[1,0]
	v_pk_mul_f32 v[106:107], v[106:107], v[18:19] op_sel_hi:[1,0]
	v_pk_mul_f32 v[108:109], v[108:109], v[18:19] op_sel_hi:[1,0]
	v_pk_mul_f32 v[110:111], v[110:111], v[18:19] op_sel_hi:[1,0]
	v_pk_mul_f32 v[112:113], v[112:113], v[18:19] op_sel_hi:[1,0]
	v_pk_mul_f32 v[114:115], v[114:115], v[18:19] op_sel_hi:[1,0]
	v_pk_mul_f32 v[116:117], v[116:117], v[18:19] op_sel_hi:[1,0]
	v_pk_mul_f32 v[118:119], v[118:119], v[18:19] op_sel_hi:[1,0]
	v_pk_mul_f32 v[104:105], v[0:1], v[104:105]
	v_pk_mul_f32 v[106:107], v[2:3], v[106:107]
	v_pk_mul_f32 v[108:109], v[4:5], v[108:109]
	v_pk_mul_f32 v[110:111], v[6:7], v[110:111]
	v_pk_mul_f32 v[112:113], v[8:9], v[112:113]
	v_pk_mul_f32 v[114:115], v[10:11], v[114:115]
	v_pk_mul_f32 v[116:117], v[12:13], v[116:117]
	v_pk_mul_f32 v[118:119], v[14:15], v[118:119]
	v_pk_fma_f32 v[104:105], v[56:57], v[104:105], v[72:73]
	v_pk_fma_f32 v[106:107], v[58:59], v[106:107], v[74:75]
	v_pk_fma_f32 v[108:109], v[60:61], v[108:109], v[76:77]
	v_pk_fma_f32 v[110:111], v[62:63], v[110:111], v[78:79]
	v_pk_fma_f32 v[112:113], v[64:65], v[112:113], v[80:81]
	v_pk_fma_f32 v[114:115], v[66:67], v[114:115], v[82:83]
	v_pk_fma_f32 v[116:117], v[68:69], v[116:117], v[84:85]
	v_pk_fma_f32 v[118:119], v[70:71], v[118:119], v[86:87]
	v_cvt_pk_bf16_f32 v32, v104, v105
	v_cvt_pk_bf16_f32 v33, v106, v107
	v_cvt_pk_bf16_f32 v34, v108, v109
	v_cvt_pk_bf16_f32 v35, v110, v111
	v_cvt_pk_bf16_f32 v36, v112, v113
	v_cvt_pk_bf16_f32 v37, v114, v115
	v_cvt_pk_bf16_f32 v38, v116, v117
	v_cvt_pk_bf16_f32 v39, v118, v119
	s_lshl_b32 s12, s8, 11
	s_add_u32 s8, s24, s12
	s_addc_u32 s9, s25, 0
	global_store_dwordx2 v17, v[32:33], s[8:9]
	global_store_dwordx2 v17, v[34:35], s[8:9] offset:512
	global_store_dwordx2 v17, v[36:37], s[8:9] offset:1024
	global_store_dwordx2 v17, v[38:39], s[8:9] offset:1536
	s_add_u32 s3, s3, 1
	s_cmp_lt_u32 s3, s10
	s_cbranch_scc1 .Lrn4_loop

; DI int otid() { int t = threadIdx.x; asm volatile("" : "+v"(t)); return t; }
; DI void finalnorm_phase(const Params& P) {
;     const int lane = otid() & 63, wave = otid() >> 6;
;     for (int row = blockIdx.x * 4 + wave; row < NLAT; row += gridDim.x * 4) {
;         float* src = P.out + (size_t)row * DM;
;         f32x4 v[4]; float ss = 0.f;
; #pragma unroll
.LBB0_1427:
	s_or_b64 exec, exec, s[0:1]
	v_mov_b32_e32 v1, v216
	s_barrier
	v_readlane_b32 s0, v251, 38
	v_ashrrev_i32_e32 v0, 6, v216
	s_nop 0
	v_add_u32_e32 v0, s0, v0
	s_mov_b32 s0, 0x10000
	v_cmp_gt_i32_e32 vcc, s0, v0
	s_and_saveexec_b64 s[0:1], vcc
	s_cbranch_execz .LBB0_1430
	s_cmpk_eq_i32 s33, 0x200
	s_cbranch_scc1 .Lfn_fast
	v_mbcnt_hi_u32_b32 v2, -1, v217
	v_and_b32_e32 v3, 64, v2
	v_add_u32_e32 v3, 64, v3
	v_xor_b32_e32 v4, 32, v2
	v_cmp_lt_i32_e32 vcc, v4, v3
	v_lshlrev_b32_e32 v1, 4, v1
	v_readlane_b32 s4, v251, 3
	v_cndmask_b32_e32 v4, v2, v4, vcc
	v_lshlrev_b32_e32 v6, 2, v4
	v_xor_b32_e32 v4, 16, v2
	v_cmp_lt_i32_e32 vcc, v4, v3
	v_mov_b32_e32 v5, 0
	v_readlane_b32 s6, v251, 5
	v_cndmask_b32_e32 v4, v2, v4, vcc
	v_lshlrev_b32_e32 v7, 2, v4
	v_xor_b32_e32 v4, 8, v2
	v_cmp_lt_i32_e32 vcc, v4, v3
	v_readlane_b32 s7, v251, 6
	s_lshl_b32 s2, s33, 2
	v_cndmask_b32_e32 v4, v2, v4, vcc
	v_lshlrev_b32_e32 v8, 2, v4
	v_xor_b32_e32 v4, 4, v2
	v_cmp_lt_i32_e32 vcc, v4, v3
	s_mov_b64 s[0:1], 0
	v_mov_b32_e32 v12, 0x358637bd
	v_cndmask_b32_e32 v4, v2, v4, vcc
	v_lshlrev_b32_e32 v9, 2, v4
	v_xor_b32_e32 v4, 2, v2
	v_cmp_lt_i32_e32 vcc, v4, v3
	s_mov_b32 s3, 0x800000
	s_mov_b32 s4, 0xffff
	v_cndmask_b32_e32 v4, v2, v4, vcc
	v_lshlrev_b32_e32 v10, 2, v4
	v_xor_b32_e32 v4, 1, v2
	v_cmp_lt_i32_e32 vcc, v4, v3
	v_readlane_b32 s5, v251, 4
	v_readlane_b32 s8, v251, 7
	v_cndmask_b32_e32 v2, v2, v4, vcc
	v_and_b32_e32 v4, 0x3f0, v1
	v_lshlrev_b32_e32 v11, 2, v2
	v_lshl_add_u64 v[2:3], s[6:7], 0, v[4:5]
	v_lshl_add_u64 v[4:5], s[48:49], 0, v[4:5]
	v_readlane_b32 s9, v251, 8
	v_readlane_b32 s10, v251, 9
	v_readlane_b32 s11, v251, 10
	v_readlane_b32 s12, v251, 11
	v_readlane_b32 s13, v251, 12
	v_readlane_b32 s14, v251, 13
	v_readlane_b32 s15, v251, 14
	v_readlane_b32 s16, v251, 15
	v_readlane_b32 s17, v251, 16
	v_readlane_b32 s18, v251, 17
	v_readlane_b32 s19, v251, 18

; DI int otid() { int t = threadIdx.x; asm volatile("" : "+v"(t)); return t; }
; DI void finalnorm_phase(const Params& P) {
;     const int lane = otid() & 63, wave = otid() >> 6;
;     for (int row = blockIdx.x * 4 + wave; row < NLAT; row += gridDim.x * 4) {
;         float* src = P.out + (size_t)row * DM;
;         f32x4 v[4]; float ss = 0.f;
; #pragma unroll
;         for (int i = 0; i < 4; ++i) { v[i] = __builtin_nontemporal_load((const f32x4*)(src + (i * 64 + lane) * 4)); ss += v[i].x * v[i].x + v[i].y * v[i].y + v[i].z * v[i].z + v[i].w * v[i].w; }
; #pragma unroll
;         for (int o = 32; o > 0; o >>= 1) ss += __shfl_xor(ss, o);
;         const float rs = rsqrtf(ss * (1.0f / 1024.0f) + EPS);
; #pragma unroll
;         for (int i = 0; i < 4; ++i) { const int col = (i * 64 + lane) * 4; *(f32x4*)(src + col) = v[i] * rs * *(const f32x4*)(P.final_gain + col); }
;     }
.Lfn_fast:
	v_lshrrev_b32_e32 v20, 6, v216
	v_and_b32_e32 v21, 63, v216
	v_mov_b32_e32 v30, 0x358637bd
	v_readfirstlane_b32 s3, v20
	v_readlane_b32 s12, v251, 38
	v_lshlrev_b32_e32 v16, 4, v21
	v_readlane_b32 s6, v251, 5
	v_readlane_b32 s7, v251, 6
	s_add_u32 s3, s3, s12
	s_lshl_b32 s3, s3, 5
	s_add_u32 s10, s3, 32
	s_nop 3
	global_load_dwordx4 v[0:3], v16, s[6:7]
	global_load_dwordx4 v[4:7], v16, s[6:7] offset:1024
	global_load_dwordx4 v[8:11], v16, s[6:7] offset:2048
	global_load_dwordx4 v[12:15], v16, s[6:7] offset:3072
	s_lshr_b32 s5, s3, 20
	s_lshl_b32 s4, s3, 12
	s_add_u32 s4, s4, s48
	s_addc_u32 s5, s5, s49
	global_load_dwordx4 v[40:43], v16, s[4:5]
	global_load_dwordx4 v[44:47], v16, s[4:5] offset:1024
	global_load_dwordx4 v[48:51], v16, s[4:5] offset:2048
	global_load_dwordx4 v[52:55], v16, s[4:5] offset:3072
	s_add_u32 s12, s3, 1
	s_lshr_b32 s5, s12, 20
	s_lshl_b32 s4, s12, 12
	s_add_u32 s4, s4, s48
	s_addc_u32 s5, s5, s49
	global_load_dwordx4 v[88:91], v16, s[4:5]
	global_load_dwordx4 v[92:95], v16, s[4:5] offset:1024
	global_load_dwordx4 v[96:99], v16, s[4:5] offset:2048
	global_load_dwordx4 v[100:103], v16, s[4:5] offset:3072
	s_mov_b32 s11, 10
.Lfn_loop:
	s_waitcnt vmcnt(4)
	s_sub_u32 s12, s10, 1
	s_add_u32 s8, s3, 2
	s_min_u32 s12, s8, s12
	s_lshr_b32 s5, s12, 20
	s_lshl_b32 s4, s12, 12
	s_add_u32 s4, s4, s48
	s_addc_u32 s5, s5, s49
	global_load_dwordx4 v[104:107], v16, s[4:5]
	global_load_dwordx4 v[108:111], v16, s[4:5] offset:1024
	global_load_dwordx4 v[112:115], v16, s[4:5] offset:2048
	global_load_dwordx4 v[116:119], v16, s[4:5] offset:3072
	v_mul_f32_e32 v20, v41, v41
	v_fmac_f32_e32 v20, v40, v40
	v_fmac_f32_e32 v20, v42, v42
	v_fmac_f32_e32 v20, v43, v43
	v_mul_f32_e32 v21, v45, v45
	v_fmac_f32_e32 v21, v44, v44
	v_fmac_f32_e32 v21, v46, v46
	v_fmac_f32_e32 v21, v47, v47
	v_mul_f32_e32 v22, v49, v49
	v_fmac_f32_e32 v22, v48, v48
	v_fmac_f32_e32 v22, v50, v50
	v_fmac_f32_e32 v22, v51, v51
	v_mul_f32_e32 v23, v53, v53
	v_fmac_f32_e32 v23, v52, v52
	v_fmac_f32_e32 v23, v54, v54
	v_fmac_f32_e32 v23, v55, v55
	v_add_f32_e32 v28, v20, v21
	v_add_f32_e32 v28, v28, v22
	v_add_f32_e32 v28, v28, v23
	s_nop 1
	v_add_f32_dpp v28, v28, v28 quad_perm:[1,0,3,2] row_mask:0xf bank_mask:0xf
	s_nop 1
	v_add_f32_dpp v28, v28, v28 quad_perm:[2,3,0,1] row_mask:0xf bank_mask:0xf
	s_nop 1
	v_add_f32_dpp v28, v28, v28 row_half_mirror row_mask:0xf bank_mask:0xf
	s_nop 1
	v_add_f32_dpp v28, v28, v28 row_mirror row_mask:0xf bank_mask:0xf
	s_nop 1
	v_readlane_b32 s8, v28, 0
	v_readlane_b32 s9, v28, 16
	v_readlane_b32 s12, v28, 32
	v_readlane_b32 s4, v28, 48
	s_nop 1
	v_mov_b32_e32 v29, s8
	v_add_f32_e32 v29, s9, v29
	v_add_f32_e32 v29, s12, v29
	v_add_f32_e32 v29, s4, v29
	v_fmamk_f32 v29, v29, 0x3a800000, v30
	v_mul_f32_e32 v31, 0x4b800000, v29
	v_cmp_gt_f32_e32 vcc, 0x800000, v29
	s_nop 1
	v_cndmask_b32_e32 v29, v29, v31, vcc
	v_rsq_f32_e32 v29, v29
	s_nop 1
	v_mul_f32_e32 v31, 0x45800000, v29
	v_cndmask_b32_e32 v18, v29, v31, vcc
	s_nop 0
	v_pk_mul_f32 v[40:41], v[40:41], v[18:19] op_sel_hi:[1,0]
	v_pk_mul_f32 v[42:43], v[42:43], v[18:19] op_sel_hi:[1,0]
	v_pk_mul_f32 v[44:45], v[44:45], v[18:19] op_sel_hi:[1,0]
	v_pk_mul_f32 v[46:47], v[46:47], v[18:19] op_sel_hi:[1,0]
	v_pk_mul_f32 v[48:49], v[48:49], v[18:19] op_sel_hi:[1,0]
	v_pk_mul_f32 v[50:51], v[50:51], v[18:19] op_sel_hi:[1,0]
	v_pk_mul_f32 v[52:53], v[52:53], v[18:19] op_sel_hi:[1,0]
	v_pk_mul_f32 v[54:55], v[54:55], v[18:19] op_sel_hi:[1,0]
	v_pk_mul_f32 v[40:41], v[0:1], v[40:41]
	v_pk_mul_f32 v[42:43], v[2:3], v[42:43]
	v_pk_mul_f32 v[44:45], v[4:5], v[44:45]
	v_pk_mul_f32 v[46:47], v[6:7], v[46:47]
	v_pk_mul_f32 v[48:49], v[8:9], v[48:49]
	v_pk_mul_f32 v[50:51], v[10:11], v[50:51]
	v_pk_mul_f32 v[52:53], v[12:13], v[52:53]
	v_pk_mul_f32 v[54:55], v[14:15], v[54:55]
	s_lshr_b32 s9, s3, 20
	s_lshl_b32 s8, s3, 12
	s_add_u32 s8, s8, s48
	s_addc_u32 s9, s9, s49
	global_store_dwordx4 v16, v[40:43], s[8:9]
	global_store_dwordx4 v16, v[44:47], s[8:9] offset:1024
	global_store_dwordx4 v16, v[48:51], s[8:9] offset:2048
	global_store_dwordx4 v16, v[52:55], s[8:9] offset:3072
	s_add_u32 s3, s3, 1
	s_waitcnt vmcnt(4)
	s_sub_u32 s12, s10, 1
	s_add_u32 s8, s3, 2
	s_min_u32 s12, s8, s12
	s_lshr_b32 s5, s12, 20
	s_lshl_b32 s4, s12, 12
	s_add_u32 s4, s4, s48
	s_addc_u32 s5, s5, s49
	global_load_dwordx4 v[40:43], v16, s[4:5]
	global_load_dwordx4 v[44:47], v16, s[4:5] offset:1024
	global_load_dwordx4 v[48:51], v16, s[4:5] offset:2048
	global_load_dwordx4 v[52:55], v16, s[4:5] offset:3072
	v_mul_f32_e32 v20, v89, v89
	v_fmac_f32_e32 v20, v88, v88
	v_fmac_f32_e32 v20, v90, v90
	v_fmac_f32_e32 v20, v91, v91
	v_mul_f32_e32 v21, v93, v93
	v_fmac_f32_e32 v21, v92, v92
	v_fmac_f32_e32 v21, v94, v94
	v_fmac_f32_e32 v21, v95, v95
	v_mul_f32_e32 v22, v97, v97
	v_fmac_f32_e32 v22, v96, v96
	v_fmac_f32_e32 v22, v98, v98
	v_fmac_f32_e32 v22, v99, v99
	v_mul_f32_e32 v23, v101, v101
	v_fmac_f32_e32 v23, v100, v100
	v_fmac_f32_e32 v23, v102, v102
	v_fmac_f32_e32 v23, v103, v103
	v_add_f32_e32 v28, v20, v21
	v_add_f32_e32 v28, v28, v22
	v_add_f32_e32 v28, v28, v23
	s_nop 1
	v_add_f32_dpp v28, v28, v28 quad_perm:[1,0,3,2] row_mask:0xf bank_mask:0xf
	s_nop 1
	v_add_f32_dpp v28, v28, v28 quad_perm:[2,3,0,1] row_mask:0xf bank_mask:0xf
	s_nop 1
	v_add_f32_dpp v28, v28, v28 row_half_mirror row_mask:0xf bank_mask:0xf
	s_nop 1
	v_add_f32_dpp v28, v28, v28 row_mirror row_mask:0xf bank_mask:0xf
	s_nop 1
	v_readlane_b32 s8, v28, 0
	v_readlane_b32 s9, v28, 16
	v_readlane_b32 s12, v28, 32
	v_readlane_b32 s4, v28, 48
	s_nop 1
	v_mov_b32_e32 v29, s8
	v_add_f32_e32 v29, s9, v29
	v_add_f32_e32 v29, s12, v29
	v_add_f32_e32 v29, s4, v29
; DI int otid() { int t = threadIdx.x; asm volatile("" : "+v"(t)); return t; }
; DI void finalnorm_phase(const Params& P) {
;     const int lane = otid() & 63, wave = otid() >> 6;
;     for (int row = blockIdx.x * 4 + wave; row < NLAT; row += gridDim.x * 4) {
;         float* src = P.out + (size_t)row * DM;
;         f32x4 v[4]; float ss = 0.f;
; #pragma unroll
;         for (int i = 0; i < 4; ++i) { v[i] = __builtin_nontemporal_load((const f32x4*)(src + (i * 64 + lane) * 4)); ss += v[i].x * v[i].x + v[i].y * v[i].y + v[i].z * v[i].z + v[i].w * v[i].w; }
; #pragma unroll
;         for (int o = 32; o > 0; o >>= 1) ss += __shfl_xor(ss, o);
;         const float rs = rsqrtf(ss * (1.0f / 1024.0f) + EPS);
; #pragma unroll
;         for (int i = 0; i < 4; ++i) { const int col = (i * 64 + lane) * 4; *(f32x4*)(src + col) = v[i] * rs * *(const f32x4*)(P.final_gain + col); }
;     }
	v_fmamk_f32 v29, v29, 0x3a800000, v30
	v_mul_f32_e32 v31, 0x4b800000, v29
	v_cmp_gt_f32_e32 vcc, 0x800000, v29
	s_nop 1
	v_cndmask_b32_e32 v29, v29, v31, vcc
	v_rsq_f32_e32 v29, v29
	s_nop 1
	v_mul_f32_e32 v31, 0x45800000, v29
	v_cndmask_b32_e32 v18, v29, v31, vcc
	s_nop 0
	v_pk_mul_f32 v[88:89], v[88:89], v[18:19] op_sel_hi:[1,0]
	v_pk_mul_f32 v[90:91], v[90:91], v[18:19] op_sel_hi:[1,0]
	v_pk_mul_f32 v[92:93], v[92:93], v[18:19] op_sel_hi:[1,0]
	v_pk_mul_f32 v[94:95], v[94:95], v[18:19] op_sel_hi:[1,0]
	v_pk_mul_f32 v[96:97], v[96:97], v[18:19] op_sel_hi:[1,0]
	v_pk_mul_f32 v[98:99], v[98:99], v[18:19] op_sel_hi:[1,0]
	v_pk_mul_f32 v[100:101], v[100:101], v[18:19] op_sel_hi:[1,0]
	v_pk_mul_f32 v[102:103], v[102:103], v[18:19] op_sel_hi:[1,0]
	v_pk_mul_f32 v[88:89], v[0:1], v[88:89]
	v_pk_mul_f32 v[90:91], v[2:3], v[90:91]
	v_pk_mul_f32 v[92:93], v[4:5], v[92:93]
	v_pk_mul_f32 v[94:95], v[6:7], v[94:95]
	v_pk_mul_f32 v[96:97], v[8:9], v[96:97]
	v_pk_mul_f32 v[98:99], v[10:11], v[98:99]
	v_pk_mul_f32 v[100:101], v[12:13], v[100:101]
	v_pk_mul_f32 v[102:103], v[14:15], v[102:103]
	s_lshr_b32 s9, s3, 20
	s_lshl_b32 s8, s3, 12
	s_add_u32 s8, s8, s48
	s_addc_u32 s9, s9, s49
	global_store_dwordx4 v16, v[88:91], s[8:9]
	global_store_dwordx4 v16, v[92:95], s[8:9] offset:1024
	global_store_dwordx4 v16, v[96:99], s[8:9] offset:2048
	global_store_dwordx4 v16, v[100:103], s[8:9] offset:3072
	s_add_u32 s3, s3, 1
	s_waitcnt vmcnt(4)
	s_sub_u32 s12, s10, 1
	s_add_u32 s8, s3, 2
	s_min_u32 s12, s8, s12
	s_lshr_b32 s5, s12, 20
	s_lshl_b32 s4, s12, 12
	s_add_u32 s4, s4, s48
	s_addc_u32 s5, s5, s49
	global_load_dwordx4 v[88:91], v16, s[4:5]
	global_load_dwordx4 v[92:95], v16, s[4:5] offset:1024
	global_load_dwordx4 v[96:99], v16, s[4:5] offset:2048
	global_load_dwordx4 v[100:103], v16, s[4:5] offset:3072
	v_mul_f32_e32 v20, v105, v105
	v_fmac_f32_e32 v20, v104, v104
	v_fmac_f32_e32 v20, v106, v106
	v_fmac_f32_e32 v20, v107, v107
	v_mul_f32_e32 v21, v109, v109
	v_fmac_f32_e32 v21, v108, v108
	v_fmac_f32_e32 v21, v110, v110
	v_fmac_f32_e32 v21, v111, v111
	v_mul_f32_e32 v22, v113, v113
	v_fmac_f32_e32 v22, v112, v112
	v_fmac_f32_e32 v22, v114, v114
	v_fmac_f32_e32 v22, v115, v115
	v_mul_f32_e32 v23, v117, v117
	v_fmac_f32_e32 v23, v116, v116
	v_fmac_f32_e32 v23, v118, v118
	v_fmac_f32_e32 v23, v119, v119
	v_add_f32_e32 v28, v20, v21
	v_add_f32_e32 v28, v28, v22
	v_add_f32_e32 v28, v28, v23
	s_nop 1
	v_add_f32_dpp v28, v28, v28 quad_perm:[1,0,3,2] row_mask:0xf bank_mask:0xf
	s_nop 1
	v_add_f32_dpp v28, v28, v28 quad_perm:[2,3,0,1] row_mask:0xf bank_mask:0xf
	s_nop 1
	v_add_f32_dpp v28, v28, v28 row_half_mirror row_mask:0xf bank_mask:0xf
	s_nop 1
	v_add_f32_dpp v28, v28, v28 row_mirror row_mask:0xf bank_mask:0xf
	s_nop 1
	v_readlane_b32 s8, v28, 0
	v_readlane_b32 s9, v28, 16
	v_readlane_b32 s12, v28, 32
	v_readlane_b32 s4, v28, 48
	s_nop 1
	v_mov_b32_e32 v29, s8
	v_add_f32_e32 v29, s9, v29
	v_add_f32_e32 v29, s12, v29
	v_add_f32_e32 v29, s4, v29
	v_fmamk_f32 v29, v29, 0x3a800000, v30
	v_mul_f32_e32 v31, 0x4b800000, v29
	v_cmp_gt_f32_e32 vcc, 0x800000, v29
	s_nop 1
	v_cndmask_b32_e32 v29, v29, v31, vcc
	v_rsq_f32_e32 v29, v29
	s_nop 1
	v_mul_f32_e32 v31, 0x45800000, v29
	v_cndmask_b32_e32 v18, v29, v31, vcc
	s_nop 0
	v_pk_mul_f32 v[104:105], v[104:105], v[18:19] op_sel_hi:[1,0]
	v_pk_mul_f32 v[106:107], v[106:107], v[18:19] op_sel_hi:[1,0]
	v_pk_mul_f32 v[108:109], v[108:109], v[18:19] op_sel_hi:[1,0]
	v_pk_mul_f32 v[110:111], v[110:111], v[18:19] op_sel_hi:[1,0]
	v_pk_mul_f32 v[112:113], v[112:113], v[18:19] op_sel_hi:[1,0]
	v_pk_mul_f32 v[114:115], v[114:115], v[18:19] op_sel_hi:[1,0]
	v_pk_mul_f32 v[116:117], v[116:117], v[18:19] op_sel_hi:[1,0]
	v_pk_mul_f32 v[118:119], v[118:119], v[18:19] op_sel_hi:[1,0]
	v_pk_mul_f32 v[104:105], v[0:1], v[104:105]
	v_pk_mul_f32 v[106:107], v[2:3], v[106:107]
	v_pk_mul_f32 v[108:109], v[4:5], v[108:109]
	v_pk_mul_f32 v[110:111], v[6:7], v[110:111]
	v_pk_mul_f32 v[112:113], v[8:9], v[112:113]
	v_pk_mul_f32 v[114:115], v[10:11], v[114:115]
	v_pk_mul_f32 v[116:117], v[12:13], v[116:117]
	v_pk_mul_f32 v[118:119], v[14:15], v[118:119]
	s_lshr_b32 s9, s3, 20
	s_lshl_b32 s8, s3, 12
	s_add_u32 s8, s8, s48
	s_addc_u32 s9, s9, s49
	global_store_dwordx4 v16, v[104:107], s[8:9]
	global_store_dwordx4 v16, v[108:111], s[8:9] offset:1024
	global_store_dwordx4 v16, v[112:115], s[8:9] offset:2048
	global_store_dwordx4 v16, v[116:119], s[8:9] offset:3072
	s_add_u32 s3, s3, 1
	s_sub_u32 s11, s11, 1
	s_cmp_lg_u32 s11, 0
	s_cbranch_scc1 .Lfn_loop
; DI int otid() { int t = threadIdx.x; asm volatile("" : "+v"(t)); return t; }
; DI void finalnorm_phase(const Params& P) {
;     const int lane = otid() & 63, wave = otid() >> 6;
;     for (int row = blockIdx.x * 4 + wave; row < NLAT; row += gridDim.x * 4) {
;         float* src = P.out + (size_t)row * DM;
;         f32x4 v[4]; float ss = 0.f;
; #pragma unroll
;         for (int i = 0; i < 4; ++i) { v[i] = __builtin_nontemporal_load((const f32x4*)(src + (i * 64 + lane) * 4)); ss += v[i].x * v[i].x + v[i].y * v[i].y + v[i].z * v[i].z + v[i].w * v[i].w; }
; #pragma unroll
;         for (int o = 32; o > 0; o >>= 1) ss += __shfl_xor(ss, o);
;         const float rs = rsqrtf(ss * (1.0f / 1024.0f) + EPS);
; #pragma unroll
;         for (int i = 0; i < 4; ++i) { const int col = (i * 64 + lane) * 4; *(f32x4*)(src + col) = v[i] * rs * *(const f32x4*)(P.final_gain + col); }
;     }
	s_waitcnt vmcnt(4)
	s_sub_u32 s12, s10, 1
	s_add_u32 s8, s3, 2
	s_min_u32 s12, s8, s12
	s_lshr_b32 s5, s12, 20
	s_lshl_b32 s4, s12, 12
	s_add_u32 s4, s4, s48
	s_addc_u32 s5, s5, s49
	global_load_dwordx4 v[104:107], v16, s[4:5]
	global_load_dwordx4 v[108:111], v16, s[4:5] offset:1024
	global_load_dwordx4 v[112:115], v16, s[4:5] offset:2048
	global_load_dwordx4 v[116:119], v16, s[4:5] offset:3072
	v_mul_f32_e32 v20, v41, v41
	v_fmac_f32_e32 v20, v40, v40
	v_fmac_f32_e32 v20, v42, v42
	v_fmac_f32_e32 v20, v43, v43
	v_mul_f32_e32 v21, v45, v45
	v_fmac_f32_e32 v21, v44, v44
	v_fmac_f32_e32 v21, v46, v46
	v_fmac_f32_e32 v21, v47, v47
	v_mul_f32_e32 v22, v49, v49
	v_fmac_f32_e32 v22, v48, v48
	v_fmac_f32_e32 v22, v50, v50
	v_fmac_f32_e32 v22, v51, v51
	v_mul_f32_e32 v23, v53, v53
	v_fmac_f32_e32 v23, v52, v52
	v_fmac_f32_e32 v23, v54, v54
	v_fmac_f32_e32 v23, v55, v55
	v_add_f32_e32 v28, v20, v21
	v_add_f32_e32 v28, v28, v22
	v_add_f32_e32 v28, v28, v23
	s_nop 1
	v_add_f32_dpp v28, v28, v28 quad_perm:[1,0,3,2] row_mask:0xf bank_mask:0xf
	s_nop 1
	v_add_f32_dpp v28, v28, v28 quad_perm:[2,3,0,1] row_mask:0xf bank_mask:0xf
	s_nop 1
	v_add_f32_dpp v28, v28, v28 row_half_mirror row_mask:0xf bank_mask:0xf
	s_nop 1
	v_add_f32_dpp v28, v28, v28 row_mirror row_mask:0xf bank_mask:0xf
	s_nop 1
	v_readlane_b32 s8, v28, 0
	v_readlane_b32 s9, v28, 16
	v_readlane_b32 s12, v28, 32
	v_readlane_b32 s4, v28, 48
	s_nop 1
	v_mov_b32_e32 v29, s8
	v_add_f32_e32 v29, s9, v29
	v_add_f32_e32 v29, s12, v29
	v_add_f32_e32 v29, s4, v29
	v_fmamk_f32 v29, v29, 0x3a800000, v30
	v_mul_f32_e32 v31, 0x4b800000, v29
	v_cmp_gt_f32_e32 vcc, 0x800000, v29
	s_nop 1
	v_cndmask_b32_e32 v29, v29, v31, vcc
	v_rsq_f32_e32 v29, v29
	s_nop 1
	v_mul_f32_e32 v31, 0x45800000, v29
	v_cndmask_b32_e32 v18, v29, v31, vcc
	s_nop 0
	v_pk_mul_f32 v[40:41], v[40:41], v[18:19] op_sel_hi:[1,0]
	v_pk_mul_f32 v[42:43], v[42:43], v[18:19] op_sel_hi:[1,0]
	v_pk_mul_f32 v[44:45], v[44:45], v[18:19] op_sel_hi:[1,0]
	v_pk_mul_f32 v[46:47], v[46:47], v[18:19] op_sel_hi:[1,0]
	v_pk_mul_f32 v[48:49], v[48:49], v[18:19] op_sel_hi:[1,0]
	v_pk_mul_f32 v[50:51], v[50:51], v[18:19] op_sel_hi:[1,0]
	v_pk_mul_f32 v[52:53], v[52:53], v[18:19] op_sel_hi:[1,0]
	v_pk_mul_f32 v[54:55], v[54:55], v[18:19] op_sel_hi:[1,0]
	v_pk_mul_f32 v[40:41], v[0:1], v[40:41]
	v_pk_mul_f32 v[42:43], v[2:3], v[42:43]
	v_pk_mul_f32 v[44:45], v[4:5], v[44:45]
	v_pk_mul_f32 v[46:47], v[6:7], v[46:47]
	v_pk_mul_f32 v[48:49], v[8:9], v[48:49]
	v_pk_mul_f32 v[50:51], v[10:11], v[50:51]
	v_pk_mul_f32 v[52:53], v[12:13], v[52:53]
	v_pk_mul_f32 v[54:55], v[14:15], v[54:55]
	s_lshr_b32 s9, s3, 20
	s_lshl_b32 s8, s3, 12
	s_add_u32 s8, s8, s48
	s_addc_u32 s9, s9, s49
	global_store_dwordx4 v16, v[40:43], s[8:9]
	global_store_dwordx4 v16, v[44:47], s[8:9] offset:1024
	global_store_dwordx4 v16, v[48:51], s[8:9] offset:2048
	global_store_dwordx4 v16, v[52:55], s[8:9] offset:3072
	s_add_u32 s3, s3, 1
	s_waitcnt vmcnt(4)
	s_sub_u32 s12, s10, 1
	s_add_u32 s8, s3, 2
	s_min_u32 s12, s8, s12
	s_lshr_b32 s5, s12, 20
	s_lshl_b32 s4, s12, 12
	s_add_u32 s4, s4, s48
	s_addc_u32 s5, s5, s49
	global_load_dwordx4 v[40:43], v16, s[4:5]
	global_load_dwordx4 v[44:47], v16, s[4:5] offset:1024
	global_load_dwordx4 v[48:51], v16, s[4:5] offset:2048
	global_load_dwordx4 v[52:55], v16, s[4:5] offset:3072
	v_mul_f32_e32 v20, v89, v89
	v_fmac_f32_e32 v20, v88, v88
	v_fmac_f32_e32 v20, v90, v90
	v_fmac_f32_e32 v20, v91, v91
	v_mul_f32_e32 v21, v93, v93
	v_fmac_f32_e32 v21, v92, v92
	v_fmac_f32_e32 v21, v94, v94
	v_fmac_f32_e32 v21, v95, v95
	v_mul_f32_e32 v22, v97, v97
	v_fmac_f32_e32 v22, v96, v96
	v_fmac_f32_e32 v22, v98, v98
	v_fmac_f32_e32 v22, v99, v99
	v_mul_f32_e32 v23, v101, v101
	v_fmac_f32_e32 v23, v100, v100
	v_fmac_f32_e32 v23, v102, v102
	v_fmac_f32_e32 v23, v103, v103
	v_add_f32_e32 v28, v20, v21
	v_add_f32_e32 v28, v28, v22
	v_add_f32_e32 v28, v28, v23
	s_nop 1
	v_add_f32_dpp v28, v28, v28 quad_perm:[1,0,3,2] row_mask:0xf bank_mask:0xf
	s_nop 1
	v_add_f32_dpp v28, v28, v28 quad_perm:[2,3,0,1] row_mask:0xf bank_mask:0xf
	s_nop 1
	v_add_f32_dpp v28, v28, v28 row_half_mirror row_mask:0xf bank_mask:0xf
	s_nop 1
	v_add_f32_dpp v28, v28, v28 row_mirror row_mask:0xf bank_mask:0xf
	s_nop 1
	v_readlane_b32 s8, v28, 0
	v_readlane_b32 s9, v28, 16
	v_readlane_b32 s12, v28, 32
	v_readlane_b32 s4, v28, 48
	s_nop 1
	v_mov_b32_e32 v29, s8
	v_add_f32_e32 v29, s9, v29
	v_add_f32_e32 v29, s12, v29
	v_add_f32_e32 v29, s4, v29
	v_fmamk_f32 v29, v29, 0x3a800000, v30
	v_mul_f32_e32 v31, 0x4b800000, v29
	v_cmp_gt_f32_e32 vcc, 0x800000, v29
	s_nop 1
	v_cndmask_b32_e32 v29, v29, v31, vcc
	v_rsq_f32_e32 v29, v29
	s_nop 1
	v_mul_f32_e32 v31, 0x45800000, v29
	v_cndmask_b32_e32 v18, v29, v31, vcc
	s_nop 0
	v_pk_mul_f32 v[88:89], v[88:89], v[18:19] op_sel_hi:[1,0]
	v_pk_mul_f32 v[90:91], v[90:91], v[18:19] op_sel_hi:[1,0]
	v_pk_mul_f32 v[92:93], v[92:93], v[18:19] op_sel_hi:[1,0]
	v_pk_mul_f32 v[94:95], v[94:95], v[18:19] op_sel_hi:[1,0]
	v_pk_mul_f32 v[96:97], v[96:97], v[18:19] op_sel_hi:[1,0]
	v_pk_mul_f32 v[98:99], v[98:99], v[18:19] op_sel_hi:[1,0]
	v_pk_mul_f32 v[100:101], v[100:101], v[18:19] op_sel_hi:[1,0]
	v_pk_mul_f32 v[102:103], v[102:103], v[18:19] op_sel_hi:[1,0]
	v_pk_mul_f32 v[88:89], v[0:1], v[88:89]
	v_pk_mul_f32 v[90:91], v[2:3], v[90:91]
	v_pk_mul_f32 v[92:93], v[4:5], v[92:93]
	v_pk_mul_f32 v[94:95], v[6:7], v[94:95]
	v_pk_mul_f32 v[96:97], v[8:9], v[96:97]
	v_pk_mul_f32 v[98:99], v[10:11], v[98:99]
	v_pk_mul_f32 v[100:101], v[12:13], v[100:101]
	v_pk_mul_f32 v[102:103], v[14:15], v[102:103]
	s_lshr_b32 s9, s3, 20
	s_lshl_b32 s8, s3, 12
	s_add_u32 s8, s8, s48
	s_addc_u32 s9, s9, s49
	global_store_dwordx4 v16, v[88:91], s[8:9]
	global_store_dwordx4 v16, v[92:95], s[8:9] offset:1024
	global_store_dwordx4 v16, v[96:99], s[8:9] offset:2048
	global_store_dwordx4 v16, v[100:103], s[8:9] offset:3072
	s_add_u32 s3, s3, 1
	s_branch .LBB0_1430
